# combined: write-through stores without L2 write-back at grid barriers, batched residual loads in LayerNorm epilogues, GEMM K-loop barrier/setprio handoff reorder
# speedup vs baseline: 1.0118x; 1.0087x over previous
.LBB0_764:
	s_add_u32 s0, s74, s24
	s_addc_u32 s1, s75, s25
	v_lshrrev_b32_e32 v130, 1, v166
	s_add_u32 s24, s0, 0x9c00000
	v_and_b32_e32 v130, 24, v130
	s_addc_u32 s25, s1, 0
	s_lshl_b32 s0, s8, 8
	v_lshl_or_b32 v130, s95, 5, v130
	v_lshl_or_b32 v131, s95, 6, v144
	s_lshl_b32 s34, s11, 8
	v_or_b32_e32 v130, s0, v130
	v_or_b32_e32 v162, s0, v131
	s_add_i32 s0, s34, s29
	v_or_b32_e32 v132, s0, v167
	v_ashrrev_i32_e32 v133, 31, v132
	v_lshlrev_b64 v[138:139], 11, v[132:133]
	v_ashrrev_i32_e32 v163, 31, v162
	v_lshl_add_u64 v[134:135], s[18:19], 0, v[138:139]
	v_lshl_add_u64 v[134:135], v[134:135], 0, v[162:163]
	s_barrier
	v_ashrrev_i32_e32 v131, 31, v130
	v_mov_b64_e32 v[248:249], v[134:135]
	v_lshl_add_u64 v[138:139], s[24:25], 0, v[138:139]
	v_lshlrev_b64 v[164:165], 1, v[130:131]
	v_lshl_add_u64 v[142:143], v[138:139], 0, v[164:165]
	v_mov_b64_e32 v[250:251], v[142:143]
	v_mov_b64_e32 v[212:213], v[248:249]
	global_load_dwordx4 v[212:215], v[212:213], off
	v_mov_b64_e32 v[216:217], v[250:251]
	global_load_dwordx4 v[216:219], v[216:217], off
	v_mov_b64_e32 v[220:221], v[250:251]
	global_load_dwordx4 v[220:223], v[220:221], off offset:256
	s_mov_b32 s98, 0x8000
	s_mov_b32 s99, 0
	v_lshl_add_u64 v[224:225], v[248:249], 0, s[98:99]
	global_load_dwordx4 v[224:227], v[224:225], off
	s_mov_b32 s98, 0x8000
	s_mov_b32 s99, 0
	v_lshl_add_u64 v[228:229], v[250:251], 0, s[98:99]
	global_load_dwordx4 v[228:231], v[228:229], off
	s_mov_b32 s98, 0x8000
	s_mov_b32 s99, 0
	v_lshl_add_u64 v[232:233], v[250:251], 0, s[98:99]
	global_load_dwordx4 v[232:235], v[232:233], off offset:256
	s_mov_b32 s98, 0x10000
	s_mov_b32 s99, 0
	v_lshl_add_u64 v[236:237], v[248:249], 0, s[98:99]
	global_load_dwordx4 v[236:239], v[236:237], off
	s_mov_b32 s98, 0x10000
	s_mov_b32 s99, 0
	v_lshl_add_u64 v[240:241], v[250:251], 0, s[98:99]
	global_load_dwordx4 v[240:243], v[240:241], off
	s_mov_b32 s98, 0x10000
	s_mov_b32 s99, 0
	v_lshl_add_u64 v[244:245], v[250:251], 0, s[98:99]
	global_load_dwordx4 v[244:247], v[244:245], off offset:256
	s_waitcnt vmcnt(0)
	v_mov_b64_e32 v[134:135], v[212:213]
	v_mov_b64_e32 v[136:137], v[214:215]
	v_mov_b64_e32 v[138:139], v[216:217]
	v_mov_b64_e32 v[140:141], v[218:219]
	s_mov_b32 s0, 0x3a000000
	v_and_b32_e32 v171, 64, v205
	v_xor_b32_e32 v170, 16, v205
	v_add_u32_e32 v171, 64, v171
	v_cmp_lt_i32_e32 vcc, v170, v171
	v_xor_b32_e32 v172, 32, v205
	v_and_b32_e32 v169, 63, v166
	v_cndmask_b32_e32 v170, v205, v170, vcc
	v_cmp_lt_i32_e32 vcc, v172, v171
	v_lshlrev_b32_e32 v170, 2, v170
	s_waitcnt vmcnt(0)
	v_cvt_pk_f32_fp8_sdwa v[146:147], v134 src0_sel:WORD_1
	v_cvt_pk_f32_fp8_e32 v[144:145], v134
	v_cvt_pk_f32_fp8_e32 v[148:149], v135
	v_cvt_pk_f32_fp8_sdwa v[134:135], v135 src0_sel:WORD_1
	v_lshlrev_b32_e32 v150, 16, v138
	v_and_b32_e32 v151, 0xffff0000, v138
	v_lshlrev_b32_e32 v138, 16, v139
	v_and_b32_e32 v139, 0xffff0000, v139
	v_pk_fma_f32 v[138:139], v[146:147], s[0:1], v[138:139] op_sel_hi:[1,0,1]
	v_lshlrev_b32_e32 v146, 16, v140
	v_and_b32_e32 v147, 0xffff0000, v140
	v_lshlrev_b32_e32 v140, 16, v141
	v_and_b32_e32 v141, 0xffff0000, v141
	v_pk_fma_f32 v[134:135], v[134:135], s[0:1], v[140:141] op_sel_hi:[1,0,1]
	v_pk_fma_f32 v[16:17], v[138:139], s[86:87], v[16:17] op_sel_hi:[1,0,1]
	s_waitcnt vmcnt(0)
	v_mov_b64_e32 v[138:139], v[220:221]
	v_mov_b64_e32 v[140:141], v[222:223]
	v_pk_fma_f32 v[12:13], v[134:135], s[86:87], v[12:13] op_sel_hi:[1,0,1]
	v_cvt_pk_f32_fp8_e32 v[134:135], v136
	v_pk_fma_f32 v[146:147], v[148:149], s[0:1], v[146:147] op_sel_hi:[1,0,1]
	v_cvt_pk_f32_fp8_sdwa v[142:143], v136 src0_sel:WORD_1
	v_pk_fma_f32 v[144:145], v[144:145], s[0:1], v[150:151] op_sel_hi:[1,0,1]
	v_pk_fma_f32 v[10:11], v[146:147], s[86:87], v[10:11] op_sel_hi:[1,0,1]
	v_pk_fma_f32 v[14:15], v[144:145], s[86:87], v[14:15] op_sel_hi:[1,0,1]
	v_cvt_pk_f32_fp8_e32 v[144:145], v137
	v_cvt_pk_f32_fp8_sdwa v[136:137], v137 src0_sel:WORD_1
	v_cndmask_b32_e32 v171, v205, v172, vcc
	v_lshlrev_b32_e32 v171, 2, v171
	v_cmp_gt_u32_e32 vcc, 16, v169
	s_waitcnt vmcnt(0)
	v_lshlrev_b32_e32 v146, 16, v138
	v_and_b32_e32 v147, 0xffff0000, v138
	v_pk_fma_f32 v[134:135], v[134:135], s[0:1], v[146:147] op_sel_hi:[1,0,1]
	v_lshlrev_b32_e32 v138, 16, v139
	v_and_b32_e32 v139, 0xffff0000, v139
	v_pk_fma_f32 v[22:23], v[134:135], s[86:87], v[22:23] op_sel_hi:[1,0,1]
	v_or_b32_e32 v134, 16, v132
	v_pk_fma_f32 v[138:139], v[142:143], s[0:1], v[138:139] op_sel_hi:[1,0,1]
	v_ashrrev_i32_e32 v135, 31, v134
	v_lshlrev_b32_e32 v142, 16, v140
	v_and_b32_e32 v143, 0xffff0000, v140
	v_lshlrev_b32_e32 v140, 16, v141
	v_and_b32_e32 v141, 0xffff0000, v141
	v_pk_fma_f32 v[24:25], v[138:139], s[86:87], v[24:25] op_sel_hi:[1,0,1]
	v_lshlrev_b64 v[138:139], 11, v[134:135]
	v_pk_fma_f32 v[142:143], v[144:145], s[0:1], v[142:143] op_sel_hi:[1,0,1]
	v_pk_fma_f32 v[136:137], v[136:137], s[0:1], v[140:141] op_sel_hi:[1,0,1]
	v_lshl_add_u64 v[134:135], s[18:19], 0, v[138:139]
	v_pk_fma_f32 v[20:21], v[136:137], s[86:87], v[20:21] op_sel_hi:[1,0,1]
	v_pk_fma_f32 v[18:19], v[142:143], s[86:87], v[18:19] op_sel_hi:[1,0,1]
	v_lshl_add_u64 v[134:135], v[134:135], 0, v[162:163]
	s_waitcnt vmcnt(0)
	v_mov_b64_e32 v[134:135], v[224:225]
	v_mov_b64_e32 v[136:137], v[226:227]
	v_lshl_add_u64 v[138:139], s[24:25], 0, v[138:139]
	v_lshl_add_u64 v[142:143], v[138:139], 0, v[164:165]
	s_waitcnt vmcnt(0)
	v_mov_b64_e32 v[138:139], v[228:229]
	v_mov_b64_e32 v[140:141], v[230:231]
	v_mov_b32_e32 v172, v15
	v_mov_b32_e32 v173, v16
	v_mov_b32_e32 v174, v14
	v_mov_b32_e32 v175, v17
	v_pk_add_f32 v[172:173], v[172:173], v[174:175]
	v_mov_b32_e32 v174, v11
	v_mov_b32_e32 v175, v12
	v_mov_b32_e32 v176, v10
	v_mov_b32_e32 v177, v13
	v_pk_add_f32 v[174:175], v[174:175], v[176:177]
	v_add_f32_e32 v172, v172, v173
	v_pk_add_f32 v[174:175], v[174:175], v[174:175] op_sel_hi:[0,1]
	v_add_f32_e32 v173, 0, v172
	v_add_f32_e32 v177, v22, v23
	v_add_f32_e32 v197, v24, v25
	v_mov_b32_e32 v176, v18
	v_mov_b32_e32 v196, v19
	v_mov_b32_e32 v174, v20
	v_mov_b32_e32 v172, v21
	v_pk_add_f32 v[176:177], v[176:177], v[196:197]
	v_pk_add_f32 v[172:173], v[174:175], v[172:173]
	s_waitcnt vmcnt(1)
	v_cvt_pk_f32_fp8_sdwa v[146:147], v134 src0_sel:WORD_1
	v_cvt_pk_f32_fp8_e32 v[144:145], v134
	v_cvt_pk_f32_fp8_e32 v[148:149], v135
	v_cvt_pk_f32_fp8_sdwa v[134:135], v135 src0_sel:WORD_1
	s_waitcnt vmcnt(0)
	v_lshlrev_b32_e32 v150, 16, v138
	v_and_b32_e32 v151, 0xffff0000, v138
	v_lshlrev_b32_e32 v138, 16, v139
	v_and_b32_e32 v139, 0xffff0000, v139
	v_pk_fma_f32 v[138:139], v[146:147], s[0:1], v[138:139] op_sel_hi:[1,0,1]
	v_lshlrev_b32_e32 v146, 16, v140
	v_and_b32_e32 v147, 0xffff0000, v140
	v_lshlrev_b32_e32 v140, 16, v141
	v_and_b32_e32 v141, 0xffff0000, v141
	v_pk_fma_f32 v[134:135], v[134:135], s[0:1], v[140:141] op_sel_hi:[1,0,1]
	v_pk_fma_f32 v[40:41], v[138:139], s[86:87], v[40:41] op_sel_hi:[1,0,1]
	s_waitcnt vmcnt(0)
	v_mov_b64_e32 v[138:139], v[232:233]
	v_mov_b64_e32 v[140:141], v[234:235]
	v_pk_fma_f32 v[36:37], v[134:135], s[86:87], v[36:37] op_sel_hi:[1,0,1]
	v_cvt_pk_f32_fp8_e32 v[134:135], v136
	v_pk_fma_f32 v[146:147], v[148:149], s[0:1], v[146:147] op_sel_hi:[1,0,1]
	v_cvt_pk_f32_fp8_sdwa v[142:143], v136 src0_sel:WORD_1
	v_pk_fma_f32 v[144:145], v[144:145], s[0:1], v[150:151] op_sel_hi:[1,0,1]
	v_pk_fma_f32 v[34:35], v[146:147], s[86:87], v[34:35] op_sel_hi:[1,0,1]
	v_pk_fma_f32 v[38:39], v[144:145], s[86:87], v[38:39] op_sel_hi:[1,0,1]
	v_cvt_pk_f32_fp8_e32 v[144:145], v137
	v_cvt_pk_f32_fp8_sdwa v[136:137], v137 src0_sel:WORD_1
	v_pk_add_f32 v[172:173], v[176:177], v[172:173]
	s_waitcnt vmcnt(0)
	v_lshlrev_b32_e32 v146, 16, v138
	v_and_b32_e32 v147, 0xffff0000, v138
	v_pk_fma_f32 v[134:135], v[134:135], s[0:1], v[146:147] op_sel_hi:[1,0,1]
	v_lshlrev_b32_e32 v138, 16, v139
	v_and_b32_e32 v139, 0xffff0000, v139
	v_pk_fma_f32 v[46:47], v[134:135], s[86:87], v[46:47] op_sel_hi:[1,0,1]
	v_or_b32_e32 v134, 32, v132
	v_pk_fma_f32 v[138:139], v[142:143], s[0:1], v[138:139] op_sel_hi:[1,0,1]
	v_ashrrev_i32_e32 v135, 31, v134
	v_lshlrev_b32_e32 v142, 16, v140
	v_and_b32_e32 v143, 0xffff0000, v140
	v_lshlrev_b32_e32 v140, 16, v141
	v_and_b32_e32 v141, 0xffff0000, v141
	v_pk_fma_f32 v[48:49], v[138:139], s[86:87], v[48:49] op_sel_hi:[1,0,1]
	v_lshlrev_b64 v[138:139], 11, v[134:135]
	v_pk_fma_f32 v[142:143], v[144:145], s[0:1], v[142:143] op_sel_hi:[1,0,1]
	v_pk_fma_f32 v[136:137], v[136:137], s[0:1], v[140:141] op_sel_hi:[1,0,1]
	v_lshl_add_u64 v[134:135], s[18:19], 0, v[138:139]
	v_pk_fma_f32 v[44:45], v[136:137], s[86:87], v[44:45] op_sel_hi:[1,0,1]
	v_pk_fma_f32 v[42:43], v[142:143], s[86:87], v[42:43] op_sel_hi:[1,0,1]
	v_lshl_add_u64 v[134:135], v[134:135], 0, v[162:163]
	s_waitcnt vmcnt(0)
	v_mov_b64_e32 v[134:135], v[236:237]
	v_mov_b64_e32 v[136:137], v[238:239]
	v_lshl_add_u64 v[138:139], s[24:25], 0, v[138:139]
	v_lshl_add_u64 v[142:143], v[138:139], 0, v[164:165]
	s_waitcnt vmcnt(0)
	v_mov_b64_e32 v[138:139], v[240:241]
	v_mov_b64_e32 v[140:141], v[242:243]
	v_add_f32_e32 v172, v172, v173
	ds_bpermute_b32 v173, v170, v172
	s_waitcnt lgkmcnt(0)
	v_add_f32_e32 v172, v172, v173
	ds_bpermute_b32 v173, v171, v172
	s_waitcnt lgkmcnt(0)
	v_add_f32_e32 v172, v172, v173
	v_fmamk_f32 v174, v172, 0xbc800000, v17
	v_fmamk_f32 v176, v172, 0xbc800000, v15
	v_fmamk_f32 v173, v172, 0xbc800000, v16
	v_fmamk_f32 v175, v172, 0xbc800000, v14
	v_mul_f32_e32 v176, v176, v176
	v_mul_f32_e32 v174, v174, v174
	v_fmac_f32_e32 v176, v175, v175
	v_fmac_f32_e32 v174, v173, v173
	v_fmamk_f32 v175, v172, 0xbc800000, v13
	v_fmamk_f32 v177, v172, 0xbc800000, v11
	v_add_f32_e32 v173, v176, v174
	v_fmamk_f32 v174, v172, 0xbc800000, v12
	v_fmamk_f32 v176, v172, 0xbc800000, v10
	v_mul_f32_e32 v177, v177, v177
	v_mul_f32_e32 v175, v175, v175
	v_fmac_f32_e32 v177, v176, v176
	v_fmac_f32_e32 v175, v174, v174
	v_add_f32_e32 v174, v177, v175
	v_fmamk_f32 v175, v172, 0xbc800000, v25
	v_fmamk_f32 v177, v172, 0xbc800000, v23
	v_add_f32_e32 v173, v173, v174
	v_fmamk_f32 v174, v172, 0xbc800000, v24
	v_fmamk_f32 v176, v172, 0xbc800000, v22
	v_mul_f32_e32 v177, v177, v177
	v_mul_f32_e32 v175, v175, v175
	v_fmac_f32_e32 v177, v176, v176
	v_fmac_f32_e32 v175, v174, v174
	v_add_f32_e32 v174, v177, v175
	v_fmamk_f32 v175, v172, 0xbc800000, v21
	v_fmamk_f32 v177, v172, 0xbc800000, v19
	v_add_f32_e32 v173, v174, v173
	v_fmamk_f32 v174, v172, 0xbc800000, v20
	v_fmamk_f32 v176, v172, 0xbc800000, v18
	v_mul_f32_e32 v177, v177, v177
	v_mul_f32_e32 v175, v175, v175
	v_fmac_f32_e32 v177, v176, v176
	v_fmac_f32_e32 v175, v174, v174
	v_add_f32_e32 v174, v177, v175
	v_add_f32_e32 v173, v174, v173
	ds_bpermute_b32 v174, v170, v173
	s_waitcnt lgkmcnt(0)
	v_add_f32_e32 v173, v173, v174
	ds_bpermute_b32 v174, v171, v173
	s_waitcnt vmcnt(1)
	v_cvt_pk_f32_fp8_sdwa v[146:147], v134 src0_sel:WORD_1
	v_cvt_pk_f32_fp8_e32 v[144:145], v134
	v_cvt_pk_f32_fp8_e32 v[148:149], v135
	v_cvt_pk_f32_fp8_sdwa v[134:135], v135 src0_sel:WORD_1
	s_waitcnt vmcnt(0)
	v_lshlrev_b32_e32 v150, 16, v138
	v_and_b32_e32 v151, 0xffff0000, v138
	v_lshlrev_b32_e32 v138, 16, v139
	v_and_b32_e32 v139, 0xffff0000, v139
	v_pk_fma_f32 v[138:139], v[146:147], s[0:1], v[138:139] op_sel_hi:[1,0,1]
	v_lshlrev_b32_e32 v146, 16, v140
	v_and_b32_e32 v147, 0xffff0000, v140
	v_lshlrev_b32_e32 v140, 16, v141
	v_and_b32_e32 v141, 0xffff0000, v141
	v_pk_fma_f32 v[134:135], v[134:135], s[0:1], v[140:141] op_sel_hi:[1,0,1]
	v_pk_fma_f32 v[64:65], v[138:139], s[86:87], v[64:65] op_sel_hi:[1,0,1]
	s_waitcnt vmcnt(0)
	v_mov_b64_e32 v[138:139], v[244:245]
	v_mov_b64_e32 v[140:141], v[246:247]
	s_mov_b32 s98, 0x18000
	s_mov_b32 s99, 0
	v_lshl_add_u64 v[212:213], v[248:249], 0, s[98:99]
	global_load_dwordx4 v[212:215], v[212:213], off
	s_mov_b32 s98, 0x18000
	s_mov_b32 s99, 0
	v_lshl_add_u64 v[216:217], v[250:251], 0, s[98:99]
	global_load_dwordx4 v[216:219], v[216:217], off
	s_mov_b32 s98, 0x18000
	s_mov_b32 s99, 0
	v_lshl_add_u64 v[220:221], v[250:251], 0, s[98:99]
	global_load_dwordx4 v[220:223], v[220:221], off offset:256
	s_mov_b32 s98, 0x40000
	s_mov_b32 s99, 0
	v_lshl_add_u64 v[224:225], v[248:249], 0, s[98:99]
	global_load_dwordx4 v[224:227], v[224:225], off
	s_mov_b32 s98, 0x40000
	s_mov_b32 s99, 0
	v_lshl_add_u64 v[228:229], v[250:251], 0, s[98:99]
	global_load_dwordx4 v[228:231], v[228:229], off
	s_mov_b32 s98, 0x40000
	s_mov_b32 s99, 0
	v_lshl_add_u64 v[232:233], v[250:251], 0, s[98:99]
	global_load_dwordx4 v[232:235], v[232:233], off offset:256
	s_mov_b32 s98, 0x48000
	s_mov_b32 s99, 0
	v_lshl_add_u64 v[236:237], v[248:249], 0, s[98:99]
	global_load_dwordx4 v[236:239], v[236:237], off
	s_mov_b32 s98, 0x48000
	s_mov_b32 s99, 0
	v_lshl_add_u64 v[240:241], v[250:251], 0, s[98:99]
	global_load_dwordx4 v[240:243], v[240:241], off
	s_mov_b32 s98, 0x48000
	s_mov_b32 s99, 0
	v_lshl_add_u64 v[244:245], v[250:251], 0, s[98:99]
	global_load_dwordx4 v[244:247], v[244:245], off offset:256
	v_pk_fma_f32 v[60:61], v[134:135], s[86:87], v[60:61] op_sel_hi:[1,0,1]
	v_cvt_pk_f32_fp8_e32 v[134:135], v136
	v_pk_fma_f32 v[146:147], v[148:149], s[0:1], v[146:147] op_sel_hi:[1,0,1]
	v_cvt_pk_f32_fp8_sdwa v[142:143], v136 src0_sel:WORD_1
	v_pk_fma_f32 v[144:145], v[144:145], s[0:1], v[150:151] op_sel_hi:[1,0,1]
	v_pk_fma_f32 v[58:59], v[146:147], s[86:87], v[58:59] op_sel_hi:[1,0,1]
	v_pk_fma_f32 v[62:63], v[144:145], s[86:87], v[62:63] op_sel_hi:[1,0,1]
	v_cvt_pk_f32_fp8_e32 v[144:145], v137
	v_cvt_pk_f32_fp8_sdwa v[136:137], v137 src0_sel:WORD_1
	s_waitcnt vmcnt(0)
	v_lshlrev_b32_e32 v146, 16, v138
	v_and_b32_e32 v147, 0xffff0000, v138
	v_pk_fma_f32 v[134:135], v[134:135], s[0:1], v[146:147] op_sel_hi:[1,0,1]
	v_lshlrev_b32_e32 v138, 16, v139
	v_and_b32_e32 v139, 0xffff0000, v139
	v_pk_fma_f32 v[70:71], v[134:135], s[86:87], v[70:71] op_sel_hi:[1,0,1]
	v_or_b32_e32 v134, 48, v132
	v_pk_fma_f32 v[138:139], v[142:143], s[0:1], v[138:139] op_sel_hi:[1,0,1]
	v_ashrrev_i32_e32 v135, 31, v134
	v_lshlrev_b32_e32 v142, 16, v140
	v_and_b32_e32 v143, 0xffff0000, v140
	v_lshlrev_b32_e32 v140, 16, v141
	v_and_b32_e32 v141, 0xffff0000, v141
	v_pk_fma_f32 v[72:73], v[138:139], s[86:87], v[72:73] op_sel_hi:[1,0,1]
	v_lshlrev_b64 v[138:139], 11, v[134:135]
	v_pk_fma_f32 v[142:143], v[144:145], s[0:1], v[142:143] op_sel_hi:[1,0,1]
	v_pk_fma_f32 v[136:137], v[136:137], s[0:1], v[140:141] op_sel_hi:[1,0,1]
	v_lshl_add_u64 v[134:135], s[18:19], 0, v[138:139]
	v_pk_fma_f32 v[68:69], v[136:137], s[86:87], v[68:69] op_sel_hi:[1,0,1]
	v_pk_fma_f32 v[66:67], v[142:143], s[86:87], v[66:67] op_sel_hi:[1,0,1]
	v_lshl_add_u64 v[134:135], v[134:135], 0, v[162:163]
	s_waitcnt vmcnt(0)
	v_mov_b64_e32 v[134:135], v[212:213]
	v_mov_b64_e32 v[136:137], v[214:215]
	v_lshl_add_u64 v[138:139], s[24:25], 0, v[138:139]
	v_lshl_add_u64 v[142:143], v[138:139], 0, v[164:165]
	s_waitcnt vmcnt(0)
	v_mov_b64_e32 v[138:139], v[216:217]
	v_mov_b64_e32 v[140:141], v[218:219]
	s_waitcnt vmcnt(1)
	v_cvt_pk_f32_fp8_sdwa v[146:147], v134 src0_sel:WORD_1
	v_cvt_pk_f32_fp8_e32 v[144:145], v134
	v_cvt_pk_f32_fp8_e32 v[148:149], v135
	v_cvt_pk_f32_fp8_sdwa v[134:135], v135 src0_sel:WORD_1
	s_waitcnt vmcnt(0)
	v_lshlrev_b32_e32 v150, 16, v138
	v_and_b32_e32 v151, 0xffff0000, v138
	v_lshlrev_b32_e32 v138, 16, v139
	v_and_b32_e32 v139, 0xffff0000, v139
	v_pk_fma_f32 v[138:139], v[146:147], s[0:1], v[138:139] op_sel_hi:[1,0,1]
	v_lshlrev_b32_e32 v146, 16, v140
	v_and_b32_e32 v147, 0xffff0000, v140
	v_lshlrev_b32_e32 v140, 16, v141
	v_and_b32_e32 v141, 0xffff0000, v141
	v_pk_fma_f32 v[134:135], v[134:135], s[0:1], v[140:141] op_sel_hi:[1,0,1]
	v_pk_fma_f32 v[88:89], v[138:139], s[86:87], v[88:89] op_sel_hi:[1,0,1]
	s_waitcnt vmcnt(0)
	v_mov_b64_e32 v[138:139], v[220:221]
	v_mov_b64_e32 v[140:141], v[222:223]
	v_pk_fma_f32 v[84:85], v[134:135], s[86:87], v[84:85] op_sel_hi:[1,0,1]
	v_cvt_pk_f32_fp8_e32 v[134:135], v136
	v_pk_fma_f32 v[146:147], v[148:149], s[0:1], v[146:147] op_sel_hi:[1,0,1]
	v_cvt_pk_f32_fp8_sdwa v[142:143], v136 src0_sel:WORD_1
	v_pk_fma_f32 v[144:145], v[144:145], s[0:1], v[150:151] op_sel_hi:[1,0,1]
	v_pk_fma_f32 v[82:83], v[146:147], s[86:87], v[82:83] op_sel_hi:[1,0,1]
	v_pk_fma_f32 v[86:87], v[144:145], s[86:87], v[86:87] op_sel_hi:[1,0,1]
	v_cvt_pk_f32_fp8_e32 v[144:145], v137
	v_cvt_pk_f32_fp8_sdwa v[136:137], v137 src0_sel:WORD_1
	s_waitcnt vmcnt(0)
	v_lshlrev_b32_e32 v146, 16, v138
	v_and_b32_e32 v147, 0xffff0000, v138
	v_pk_fma_f32 v[134:135], v[134:135], s[0:1], v[146:147] op_sel_hi:[1,0,1]
	v_lshlrev_b32_e32 v138, 16, v139
	v_and_b32_e32 v139, 0xffff0000, v139
	v_pk_fma_f32 v[94:95], v[134:135], s[86:87], v[94:95] op_sel_hi:[1,0,1]
	v_add_u32_e32 v134, 0x80, v132
	v_pk_fma_f32 v[138:139], v[142:143], s[0:1], v[138:139] op_sel_hi:[1,0,1]
	v_ashrrev_i32_e32 v135, 31, v134
	v_lshlrev_b32_e32 v142, 16, v140
	v_and_b32_e32 v143, 0xffff0000, v140
	v_lshlrev_b32_e32 v140, 16, v141
	v_and_b32_e32 v141, 0xffff0000, v141
	v_pk_fma_f32 v[96:97], v[138:139], s[86:87], v[96:97] op_sel_hi:[1,0,1]
	v_lshlrev_b64 v[138:139], 11, v[134:135]
	v_pk_fma_f32 v[142:143], v[144:145], s[0:1], v[142:143] op_sel_hi:[1,0,1]
	v_pk_fma_f32 v[136:137], v[136:137], s[0:1], v[140:141] op_sel_hi:[1,0,1]
	v_lshl_add_u64 v[134:135], s[18:19], 0, v[138:139]
	v_pk_fma_f32 v[92:93], v[136:137], s[86:87], v[92:93] op_sel_hi:[1,0,1]
	v_pk_fma_f32 v[90:91], v[142:143], s[86:87], v[90:91] op_sel_hi:[1,0,1]
	v_lshl_add_u64 v[134:135], v[134:135], 0, v[162:163]
	s_waitcnt vmcnt(0)
	v_mov_b64_e32 v[134:135], v[224:225]
	v_mov_b64_e32 v[136:137], v[226:227]
	v_lshl_add_u64 v[138:139], s[24:25], 0, v[138:139]
	v_lshl_add_u64 v[142:143], v[138:139], 0, v[164:165]
	s_waitcnt vmcnt(0)
	v_mov_b64_e32 v[138:139], v[228:229]
	v_mov_b64_e32 v[140:141], v[230:231]
	s_waitcnt vmcnt(1)
	v_cvt_pk_f32_fp8_sdwa v[146:147], v134 src0_sel:WORD_1
	v_cvt_pk_f32_fp8_e32 v[144:145], v134
	v_cvt_pk_f32_fp8_e32 v[148:149], v135
	v_cvt_pk_f32_fp8_sdwa v[134:135], v135 src0_sel:WORD_1
	s_waitcnt vmcnt(0)
	v_lshlrev_b32_e32 v150, 16, v138
	v_and_b32_e32 v151, 0xffff0000, v138
	v_lshlrev_b32_e32 v138, 16, v139
	v_and_b32_e32 v139, 0xffff0000, v139
	v_pk_fma_f32 v[138:139], v[146:147], s[0:1], v[138:139] op_sel_hi:[1,0,1]
	v_lshlrev_b32_e32 v146, 16, v140
	v_and_b32_e32 v147, 0xffff0000, v140
	v_lshlrev_b32_e32 v140, 16, v141
	v_and_b32_e32 v141, 0xffff0000, v141
	v_pk_fma_f32 v[134:135], v[134:135], s[0:1], v[140:141] op_sel_hi:[1,0,1]
	v_pk_fma_f32 v[120:121], v[138:139], s[86:87], v[120:121] op_sel_hi:[1,0,1]
	s_waitcnt vmcnt(0)
	v_mov_b64_e32 v[138:139], v[232:233]
	v_mov_b64_e32 v[140:141], v[234:235]
	v_pk_fma_f32 v[116:117], v[134:135], s[86:87], v[116:117] op_sel_hi:[1,0,1]
	v_cvt_pk_f32_fp8_e32 v[134:135], v136
	v_pk_fma_f32 v[146:147], v[148:149], s[0:1], v[146:147] op_sel_hi:[1,0,1]
	v_cvt_pk_f32_fp8_sdwa v[142:143], v136 src0_sel:WORD_1
	v_pk_fma_f32 v[144:145], v[144:145], s[0:1], v[150:151] op_sel_hi:[1,0,1]
	v_pk_fma_f32 v[114:115], v[146:147], s[86:87], v[114:115] op_sel_hi:[1,0,1]
	v_pk_fma_f32 v[118:119], v[144:145], s[86:87], v[118:119] op_sel_hi:[1,0,1]
	v_cvt_pk_f32_fp8_e32 v[144:145], v137
	v_cvt_pk_f32_fp8_sdwa v[136:137], v137 src0_sel:WORD_1
	s_waitcnt vmcnt(0)
	v_lshlrev_b32_e32 v146, 16, v138
	v_and_b32_e32 v147, 0xffff0000, v138
	v_pk_fma_f32 v[134:135], v[134:135], s[0:1], v[146:147] op_sel_hi:[1,0,1]
	v_lshlrev_b32_e32 v138, 16, v139
	v_and_b32_e32 v139, 0xffff0000, v139
	v_pk_fma_f32 v[126:127], v[134:135], s[86:87], v[126:127] op_sel_hi:[1,0,1]
	v_add_u32_e32 v134, 0x90, v132
	v_pk_fma_f32 v[138:139], v[142:143], s[0:1], v[138:139] op_sel_hi:[1,0,1]
	v_ashrrev_i32_e32 v135, 31, v134
	v_lshlrev_b32_e32 v142, 16, v140
	v_and_b32_e32 v143, 0xffff0000, v140
	v_lshlrev_b32_e32 v140, 16, v141
	v_and_b32_e32 v141, 0xffff0000, v141
	v_pk_fma_f32 v[128:129], v[138:139], s[86:87], v[128:129] op_sel_hi:[1,0,1]
	v_lshlrev_b64 v[138:139], 11, v[134:135]
	v_pk_fma_f32 v[142:143], v[144:145], s[0:1], v[142:143] op_sel_hi:[1,0,1]
	v_pk_fma_f32 v[136:137], v[136:137], s[0:1], v[140:141] op_sel_hi:[1,0,1]
	v_lshl_add_u64 v[134:135], s[18:19], 0, v[138:139]
	v_pk_fma_f32 v[124:125], v[136:137], s[86:87], v[124:125] op_sel_hi:[1,0,1]
	v_pk_fma_f32 v[122:123], v[142:143], s[86:87], v[122:123] op_sel_hi:[1,0,1]
	v_lshl_add_u64 v[134:135], v[134:135], 0, v[162:163]
	s_waitcnt vmcnt(0)
	v_mov_b64_e32 v[134:135], v[236:237]
	v_mov_b64_e32 v[136:137], v[238:239]
	v_lshl_add_u64 v[138:139], s[24:25], 0, v[138:139]
	v_lshl_add_u64 v[142:143], v[138:139], 0, v[164:165]
	s_waitcnt vmcnt(0)
	v_mov_b64_e32 v[138:139], v[240:241]
	v_mov_b64_e32 v[140:141], v[242:243]
	s_waitcnt vmcnt(1)
	v_cvt_pk_f32_fp8_sdwa v[146:147], v134 src0_sel:WORD_1
	v_cvt_pk_f32_fp8_e32 v[144:145], v134
	v_cvt_pk_f32_fp8_e32 v[148:149], v135
	v_cvt_pk_f32_fp8_sdwa v[134:135], v135 src0_sel:WORD_1
	s_waitcnt vmcnt(0)
	v_lshlrev_b32_e32 v150, 16, v138
	v_and_b32_e32 v151, 0xffff0000, v138
	v_lshlrev_b32_e32 v138, 16, v139
	v_and_b32_e32 v139, 0xffff0000, v139
	v_pk_fma_f32 v[138:139], v[146:147], s[0:1], v[138:139] op_sel_hi:[1,0,1]
	v_lshlrev_b32_e32 v146, 16, v140
	v_and_b32_e32 v147, 0xffff0000, v140
	v_lshlrev_b32_e32 v140, 16, v141
	v_and_b32_e32 v141, 0xffff0000, v141
	v_pk_fma_f32 v[134:135], v[134:135], s[0:1], v[140:141] op_sel_hi:[1,0,1]
	v_pk_fma_f32 v[112:113], v[138:139], s[86:87], v[112:113] op_sel_hi:[1,0,1]
	s_waitcnt vmcnt(0)
	v_mov_b64_e32 v[138:139], v[244:245]
	v_mov_b64_e32 v[140:141], v[246:247]
	s_mov_b32 s98, 0x50000
	s_mov_b32 s99, 0
	v_lshl_add_u64 v[212:213], v[248:249], 0, s[98:99]
	global_load_dwordx4 v[212:215], v[212:213], off
	s_mov_b32 s98, 0x50000
	s_mov_b32 s99, 0
	v_lshl_add_u64 v[216:217], v[250:251], 0, s[98:99]
	global_load_dwordx4 v[216:219], v[216:217], off
	s_mov_b32 s98, 0x50000
	s_mov_b32 s99, 0
	v_lshl_add_u64 v[220:221], v[250:251], 0, s[98:99]
	global_load_dwordx4 v[220:223], v[220:221], off offset:256
	s_mov_b32 s98, 0x58000
	s_mov_b32 s99, 0
	v_lshl_add_u64 v[224:225], v[248:249], 0, s[98:99]
	global_load_dwordx4 v[224:227], v[224:225], off
	s_mov_b32 s98, 0x58000
	s_mov_b32 s99, 0
	v_lshl_add_u64 v[228:229], v[250:251], 0, s[98:99]
	global_load_dwordx4 v[228:231], v[228:229], off
	s_mov_b32 s98, 0x58000
	s_mov_b32 s99, 0
	v_lshl_add_u64 v[232:233], v[250:251], 0, s[98:99]
	global_load_dwordx4 v[232:235], v[232:233], off offset:256
	v_pk_fma_f32 v[108:109], v[134:135], s[86:87], v[108:109] op_sel_hi:[1,0,1]
	v_cvt_pk_f32_fp8_e32 v[134:135], v136
	v_pk_fma_f32 v[146:147], v[148:149], s[0:1], v[146:147] op_sel_hi:[1,0,1]
	v_cvt_pk_f32_fp8_sdwa v[142:143], v136 src0_sel:WORD_1
	v_pk_fma_f32 v[144:145], v[144:145], s[0:1], v[150:151] op_sel_hi:[1,0,1]
	v_pk_fma_f32 v[106:107], v[146:147], s[86:87], v[106:107] op_sel_hi:[1,0,1]
	v_pk_fma_f32 v[110:111], v[144:145], s[86:87], v[110:111] op_sel_hi:[1,0,1]
	v_cvt_pk_f32_fp8_e32 v[144:145], v137
	v_cvt_pk_f32_fp8_sdwa v[136:137], v137 src0_sel:WORD_1
	s_waitcnt vmcnt(0)
	v_lshlrev_b32_e32 v146, 16, v138
	v_and_b32_e32 v147, 0xffff0000, v138
	v_pk_fma_f32 v[134:135], v[134:135], s[0:1], v[146:147] op_sel_hi:[1,0,1]
	v_lshlrev_b32_e32 v138, 16, v139
	v_and_b32_e32 v139, 0xffff0000, v139
	v_pk_fma_f32 v[102:103], v[134:135], s[86:87], v[102:103] op_sel_hi:[1,0,1]
	v_add_u32_e32 v134, 0xa0, v132
	v_pk_fma_f32 v[138:139], v[142:143], s[0:1], v[138:139] op_sel_hi:[1,0,1]
	v_ashrrev_i32_e32 v135, 31, v134
	v_lshlrev_b32_e32 v142, 16, v140
	v_and_b32_e32 v143, 0xffff0000, v140
	v_lshlrev_b32_e32 v140, 16, v141
	v_and_b32_e32 v141, 0xffff0000, v141
	v_pk_fma_f32 v[104:105], v[138:139], s[86:87], v[104:105] op_sel_hi:[1,0,1]
	v_lshlrev_b64 v[138:139], 11, v[134:135]
	v_pk_fma_f32 v[142:143], v[144:145], s[0:1], v[142:143] op_sel_hi:[1,0,1]
	v_pk_fma_f32 v[136:137], v[136:137], s[0:1], v[140:141] op_sel_hi:[1,0,1]
	v_lshl_add_u64 v[134:135], s[18:19], 0, v[138:139]
	v_pk_fma_f32 v[100:101], v[136:137], s[86:87], v[100:101] op_sel_hi:[1,0,1]
	v_pk_fma_f32 v[98:99], v[142:143], s[86:87], v[98:99] op_sel_hi:[1,0,1]
	v_lshl_add_u64 v[134:135], v[134:135], 0, v[162:163]
	s_waitcnt vmcnt(0)
	v_mov_b64_e32 v[134:135], v[212:213]
	v_mov_b64_e32 v[136:137], v[214:215]
	v_lshl_add_u64 v[138:139], s[24:25], 0, v[138:139]
	v_lshl_add_u64 v[142:143], v[138:139], 0, v[164:165]
	s_waitcnt vmcnt(0)
	v_mov_b64_e32 v[138:139], v[216:217]
	v_mov_b64_e32 v[140:141], v[218:219]
	v_add_u32_e32 v132, 0xb0, v132
	v_ashrrev_i32_e32 v133, 31, v132
	s_waitcnt vmcnt(1)
	v_cvt_pk_f32_fp8_sdwa v[146:147], v134 src0_sel:WORD_1
	v_cvt_pk_f32_fp8_e32 v[144:145], v134
	v_cvt_pk_f32_fp8_e32 v[148:149], v135
	v_cvt_pk_f32_fp8_sdwa v[134:135], v135 src0_sel:WORD_1
	s_waitcnt vmcnt(0)
	v_lshlrev_b32_e32 v150, 16, v138
	v_and_b32_e32 v151, 0xffff0000, v138
	v_lshlrev_b32_e32 v138, 16, v139
	v_and_b32_e32 v139, 0xffff0000, v139
	v_pk_fma_f32 v[138:139], v[146:147], s[0:1], v[138:139] op_sel_hi:[1,0,1]
	v_lshlrev_b32_e32 v146, 16, v140
	v_and_b32_e32 v147, 0xffff0000, v140
	v_lshlrev_b32_e32 v140, 16, v141
	v_and_b32_e32 v141, 0xffff0000, v141
	v_pk_fma_f32 v[134:135], v[134:135], s[0:1], v[140:141] op_sel_hi:[1,0,1]
	v_pk_fma_f32 v[80:81], v[138:139], s[86:87], v[80:81] op_sel_hi:[1,0,1]
	s_waitcnt vmcnt(0)
	v_mov_b64_e32 v[138:139], v[220:221]
	v_mov_b64_e32 v[140:141], v[222:223]
	v_pk_fma_f32 v[144:145], v[144:145], s[0:1], v[150:151] op_sel_hi:[1,0,1]
	v_cvt_pk_f32_fp8_sdwa v[142:143], v136 src0_sel:WORD_1
	v_pk_fma_f32 v[78:79], v[144:145], s[86:87], v[78:79] op_sel_hi:[1,0,1]
	v_pk_fma_f32 v[76:77], v[134:135], s[86:87], v[76:77] op_sel_hi:[1,0,1]
	v_cvt_pk_f32_fp8_e32 v[134:135], v136
	v_cvt_pk_f32_fp8_e32 v[144:145], v137
	v_cvt_pk_f32_fp8_sdwa v[136:137], v137 src0_sel:WORD_1
	v_pk_fma_f32 v[146:147], v[148:149], s[0:1], v[146:147] op_sel_hi:[1,0,1]
	s_nop 0
	v_pk_fma_f32 v[74:75], v[146:147], s[86:87], v[74:75] op_sel_hi:[1,0,1]
	s_waitcnt vmcnt(0)
	v_lshlrev_b32_e32 v146, 16, v138
	v_and_b32_e32 v147, 0xffff0000, v138
	v_lshlrev_b32_e32 v138, 16, v139
	v_and_b32_e32 v139, 0xffff0000, v139
	v_pk_fma_f32 v[138:139], v[142:143], s[0:1], v[138:139] op_sel_hi:[1,0,1]
	v_lshlrev_b32_e32 v142, 16, v140
	v_and_b32_e32 v143, 0xffff0000, v140
	v_lshlrev_b32_e32 v140, 16, v141
	v_and_b32_e32 v141, 0xffff0000, v141
	v_pk_fma_f32 v[136:137], v[136:137], s[0:1], v[140:141] op_sel_hi:[1,0,1]
	v_pk_fma_f32 v[134:135], v[134:135], s[0:1], v[146:147] op_sel_hi:[1,0,1]
	v_pk_fma_f32 v[52:53], v[136:137], s[86:87], v[52:53] op_sel_hi:[1,0,1]
	v_lshlrev_b64 v[136:137], 11, v[132:133]
	v_pk_fma_f32 v[142:143], v[144:145], s[0:1], v[142:143] op_sel_hi:[1,0,1]
	v_lshl_add_u64 v[132:133], s[18:19], 0, v[136:137]
	v_pk_fma_f32 v[56:57], v[138:139], s[86:87], v[56:57] op_sel_hi:[1,0,1]
	v_pk_fma_f32 v[54:55], v[134:135], s[86:87], v[54:55] op_sel_hi:[1,0,1]
	v_pk_fma_f32 v[50:51], v[142:143], s[86:87], v[50:51] op_sel_hi:[1,0,1]
	v_lshl_add_u64 v[132:133], v[132:133], 0, v[162:163]
	s_waitcnt vmcnt(0)
	v_mov_b64_e32 v[132:133], v[224:225]
	v_mov_b64_e32 v[134:135], v[226:227]
	v_lshl_add_u64 v[136:137], s[24:25], 0, v[136:137]
	v_lshl_add_u64 v[140:141], v[136:137], 0, v[164:165]
	s_waitcnt vmcnt(0)
	v_mov_b64_e32 v[136:137], v[228:229]
	v_mov_b64_e32 v[138:139], v[230:231]
	s_waitcnt vmcnt(1)
	v_cvt_pk_f32_fp8_sdwa v[144:145], v132 src0_sel:WORD_1
	v_cvt_pk_f32_fp8_e32 v[142:143], v132
	v_cvt_pk_f32_fp8_e32 v[146:147], v133
	v_cvt_pk_f32_fp8_sdwa v[132:133], v133 src0_sel:WORD_1
	s_waitcnt vmcnt(0)
	v_lshlrev_b32_e32 v148, 16, v136
	v_and_b32_e32 v149, 0xffff0000, v136
	v_lshlrev_b32_e32 v136, 16, v137
	v_and_b32_e32 v137, 0xffff0000, v137
	v_pk_fma_f32 v[136:137], v[144:145], s[0:1], v[136:137] op_sel_hi:[1,0,1]
	v_lshlrev_b32_e32 v144, 16, v138
	v_and_b32_e32 v145, 0xffff0000, v138
	v_lshlrev_b32_e32 v138, 16, v139
	v_and_b32_e32 v139, 0xffff0000, v139
	v_pk_fma_f32 v[132:133], v[132:133], s[0:1], v[138:139] op_sel_hi:[1,0,1]
	v_pk_fma_f32 v[32:33], v[136:137], s[86:87], v[32:33] op_sel_hi:[1,0,1]
	s_waitcnt vmcnt(0)
	v_mov_b64_e32 v[136:137], v[232:233]
	v_mov_b64_e32 v[138:139], v[234:235]
	v_pk_fma_f32 v[142:143], v[142:143], s[0:1], v[148:149] op_sel_hi:[1,0,1]
	v_cvt_pk_f32_fp8_sdwa v[140:141], v134 src0_sel:WORD_1
	v_pk_fma_f32 v[30:31], v[142:143], s[86:87], v[30:31] op_sel_hi:[1,0,1]
	v_pk_fma_f32 v[28:29], v[132:133], s[86:87], v[28:29] op_sel_hi:[1,0,1]
	v_cvt_pk_f32_fp8_e32 v[132:133], v134
	v_cvt_pk_f32_fp8_e32 v[142:143], v135
	v_cvt_pk_f32_fp8_sdwa v[134:135], v135 src0_sel:WORD_1
	v_pk_fma_f32 v[144:145], v[146:147], s[0:1], v[144:145] op_sel_hi:[1,0,1]
	s_nop 0
	v_pk_fma_f32 v[26:27], v[144:145], s[86:87], v[26:27] op_sel_hi:[1,0,1]
	s_waitcnt vmcnt(0)
	v_lshlrev_b32_e32 v144, 16, v136
	v_and_b32_e32 v145, 0xffff0000, v136
	v_lshlrev_b32_e32 v136, 16, v137
	v_and_b32_e32 v137, 0xffff0000, v137
	v_pk_fma_f32 v[136:137], v[140:141], s[0:1], v[136:137] op_sel_hi:[1,0,1]
	v_lshlrev_b32_e32 v140, 16, v138
	v_and_b32_e32 v141, 0xffff0000, v138
	v_lshlrev_b32_e32 v138, 16, v139
	v_and_b32_e32 v139, 0xffff0000, v139
	v_pk_fma_f32 v[132:133], v[132:133], s[0:1], v[144:145] op_sel_hi:[1,0,1]
	v_pk_fma_f32 v[140:141], v[142:143], s[0:1], v[140:141] op_sel_hi:[1,0,1]
	v_pk_fma_f32 v[138:139], v[134:135], s[0:1], v[138:139] op_sel_hi:[1,0,1]
	v_readlane_b32 s0, v255, 18
	v_pk_fma_f32 v[134:135], v[132:133], s[86:87], v[6:7] op_sel_hi:[1,0,1]
	v_lshlrev_b64 v[6:7], 2, v[130:131]
	v_readlane_b32 s1, v255, 19
	v_pk_fma_f32 v[136:137], v[136:137], s[86:87], v[8:9] op_sel_hi:[1,0,1]
	v_pk_fma_f32 v[4:5], v[138:139], s[86:87], v[4:5] op_sel_hi:[1,0,1]
	v_lshl_add_u64 v[130:131], s[0:1], 0, v[6:7]
	v_readlane_b32 s0, v255, 27
	v_readlane_b32 s1, v255, 28
	v_pk_fma_f32 v[2:3], v[140:141], s[86:87], v[2:3] op_sel_hi:[1,0,1]
	s_nop 0
	v_lshl_add_u64 v[142:143], s[0:1], 0, v[6:7]
	global_load_dwordx4 v[146:149], v[130:131], off offset:16
	global_load_dwordx4 v[154:157], v[130:131], off
	global_load_dwordx4 v[150:153], v[142:143], off offset:16
	global_load_dwordx4 v[158:161], v[142:143], off
	global_load_dwordx4 v[6:9], v[130:131], off offset:528
	global_load_dwordx4 v[138:141], v[130:131], off offset:512
	s_nop 0
	global_load_dwordx4 v[130:133], v[142:143], off offset:528
	s_nop 0
	global_load_dwordx4 v[142:145], v[142:143], off offset:512
	s_lshl_b32 s0, s95, 3
	s_add_i32 s4, s0, 0
	s_and_saveexec_b64 s[0:1], vcc
	v_readlane_b32 s13, v255, 29
	s_cbranch_execz .LBB0_766
	s_lshl_b32 s5, s10, 11
	s_add_i32 s5, s4, s5
	v_mul_f32_e32 v172, 0x3c800000, v172
	v_lshl_add_u32 v175, v167, 5, s5
	s_waitcnt lgkmcnt(0)
	v_add_f32_e32 v173, v173, v174
	ds_write_b64 v175, v[172:173]

.LBB0_1026:
	s_add_u32 s4, s74, s88
	v_lshrrev_b32_e32 v130, 1, v166
	s_addc_u32 s5, s75, s89
	v_and_b32_e32 v130, 24, v130
	s_add_u32 s88, s4, 0x9c00000
	s_addc_u32 s89, s5, 0
	s_lshl_b32 s4, s0, 8
	v_lshl_or_b32 v130, s1, 5, v130
	v_lshl_or_b32 v131, s1, 6, v144
	s_lshl_b32 s11, s10, 8
	v_or_b32_e32 v130, s4, v130
	v_or_b32_e32 v162, s4, v131
	s_add_i32 s4, s11, s96
	v_or_b32_e32 v132, s4, v167
	v_ashrrev_i32_e32 v133, 31, v132
	v_lshlrev_b64 v[138:139], 11, v[132:133]
	v_ashrrev_i32_e32 v163, 31, v162
	v_lshl_add_u64 v[134:135], s[92:93], 0, v[138:139]
	v_lshl_add_u64 v[134:135], v[134:135], 0, v[162:163]
	s_barrier
	v_ashrrev_i32_e32 v131, 31, v130
	v_mov_b64_e32 v[248:249], v[134:135]
	v_lshl_add_u64 v[138:139], s[88:89], 0, v[138:139]
	v_lshlrev_b64 v[164:165], 1, v[130:131]
	v_lshl_add_u64 v[142:143], v[138:139], 0, v[164:165]
	v_mov_b64_e32 v[250:251], v[142:143]
	v_mov_b64_e32 v[212:213], v[248:249]
	global_load_dwordx4 v[212:215], v[212:213], off
	v_mov_b64_e32 v[216:217], v[250:251]
	global_load_dwordx4 v[216:219], v[216:217], off
	v_mov_b64_e32 v[220:221], v[250:251]
	global_load_dwordx4 v[220:223], v[220:221], off offset:256
	s_mov_b32 s98, 0x8000
	s_mov_b32 s99, 0
	v_lshl_add_u64 v[224:225], v[248:249], 0, s[98:99]
	global_load_dwordx4 v[224:227], v[224:225], off
	s_mov_b32 s98, 0x8000
	s_mov_b32 s99, 0
	v_lshl_add_u64 v[228:229], v[250:251], 0, s[98:99]
	global_load_dwordx4 v[228:231], v[228:229], off
	s_mov_b32 s98, 0x8000
	s_mov_b32 s99, 0
	v_lshl_add_u64 v[232:233], v[250:251], 0, s[98:99]
	global_load_dwordx4 v[232:235], v[232:233], off offset:256
	s_mov_b32 s98, 0x10000
	s_mov_b32 s99, 0
	v_lshl_add_u64 v[236:237], v[248:249], 0, s[98:99]
	global_load_dwordx4 v[236:239], v[236:237], off
	s_mov_b32 s98, 0x10000
	s_mov_b32 s99, 0
	v_lshl_add_u64 v[240:241], v[250:251], 0, s[98:99]
	global_load_dwordx4 v[240:243], v[240:241], off
	s_mov_b32 s98, 0x10000
	s_mov_b32 s99, 0
	v_lshl_add_u64 v[244:245], v[250:251], 0, s[98:99]
	global_load_dwordx4 v[244:247], v[244:245], off offset:256
	s_waitcnt vmcnt(0)
	v_mov_b64_e32 v[134:135], v[212:213]
	v_mov_b64_e32 v[136:137], v[214:215]
	v_mov_b64_e32 v[138:139], v[216:217]
	v_mov_b64_e32 v[140:141], v[218:219]
	s_mov_b32 s4, 0x3a000000
	v_readlane_b32 s6, v255, 27
	v_lshlrev_b64 v[130:131], 2, v[130:131]
	v_readlane_b32 s7, v255, 28
	v_and_b32_e32 v171, 64, v205
	v_xor_b32_e32 v170, 16, v205
	v_add_u32_e32 v171, 64, v171
	v_xor_b32_e32 v172, 32, v205
	v_and_b32_e32 v169, 63, v166
	s_lshl_b32 s1, s1, 3
	s_add_i32 s1, s1, 0
	s_waitcnt vmcnt(0)
	v_cvt_pk_f32_fp8_sdwa v[146:147], v134 src0_sel:WORD_1
	v_cvt_pk_f32_fp8_e32 v[144:145], v134
	v_cvt_pk_f32_fp8_e32 v[148:149], v135
	v_cvt_pk_f32_fp8_sdwa v[134:135], v135 src0_sel:WORD_1
	v_lshlrev_b32_e32 v150, 16, v138
	v_and_b32_e32 v151, 0xffff0000, v138
	v_lshlrev_b32_e32 v138, 16, v139
	v_and_b32_e32 v139, 0xffff0000, v139
	v_pk_fma_f32 v[138:139], v[146:147], s[4:5], v[138:139] op_sel_hi:[1,0,1]
	v_lshlrev_b32_e32 v146, 16, v140
	v_and_b32_e32 v147, 0xffff0000, v140
	v_lshlrev_b32_e32 v140, 16, v141
	v_and_b32_e32 v141, 0xffff0000, v141
	v_pk_fma_f32 v[134:135], v[134:135], s[4:5], v[140:141] op_sel_hi:[1,0,1]
	v_pk_fma_f32 v[8:9], v[138:139], s[86:87], v[8:9] op_sel_hi:[1,0,1]
	s_waitcnt vmcnt(0)
	v_mov_b64_e32 v[138:139], v[220:221]
	v_mov_b64_e32 v[140:141], v[222:223]
	v_pk_fma_f32 v[4:5], v[134:135], s[86:87], v[4:5] op_sel_hi:[1,0,1]
	v_cvt_pk_f32_fp8_e32 v[134:135], v136
	v_pk_fma_f32 v[146:147], v[148:149], s[4:5], v[146:147] op_sel_hi:[1,0,1]
	v_cvt_pk_f32_fp8_sdwa v[142:143], v136 src0_sel:WORD_1
	v_pk_fma_f32 v[144:145], v[144:145], s[4:5], v[150:151] op_sel_hi:[1,0,1]
	v_pk_fma_f32 v[2:3], v[146:147], s[86:87], v[2:3] op_sel_hi:[1,0,1]
	v_pk_fma_f32 v[6:7], v[144:145], s[86:87], v[6:7] op_sel_hi:[1,0,1]
	v_cvt_pk_f32_fp8_e32 v[144:145], v137
	v_cvt_pk_f32_fp8_sdwa v[136:137], v137 src0_sel:WORD_1
	s_waitcnt vmcnt(0)
	v_lshlrev_b32_e32 v146, 16, v138
	v_and_b32_e32 v147, 0xffff0000, v138
	v_pk_fma_f32 v[134:135], v[134:135], s[4:5], v[146:147] op_sel_hi:[1,0,1]
	v_lshlrev_b32_e32 v138, 16, v139
	v_and_b32_e32 v139, 0xffff0000, v139
	v_pk_fma_f32 v[14:15], v[134:135], s[86:87], v[14:15] op_sel_hi:[1,0,1]
	v_or_b32_e32 v134, 16, v132
	v_pk_fma_f32 v[138:139], v[142:143], s[4:5], v[138:139] op_sel_hi:[1,0,1]
	v_ashrrev_i32_e32 v135, 31, v134
	v_lshlrev_b32_e32 v142, 16, v140
	v_and_b32_e32 v143, 0xffff0000, v140
	v_lshlrev_b32_e32 v140, 16, v141
	v_and_b32_e32 v141, 0xffff0000, v141
	v_pk_fma_f32 v[16:17], v[138:139], s[86:87], v[16:17] op_sel_hi:[1,0,1]
	v_lshlrev_b64 v[138:139], 11, v[134:135]
	v_pk_fma_f32 v[142:143], v[144:145], s[4:5], v[142:143] op_sel_hi:[1,0,1]
	v_pk_fma_f32 v[136:137], v[136:137], s[4:5], v[140:141] op_sel_hi:[1,0,1]
	v_lshl_add_u64 v[134:135], s[92:93], 0, v[138:139]
	v_pk_fma_f32 v[12:13], v[136:137], s[86:87], v[12:13] op_sel_hi:[1,0,1]
	v_pk_fma_f32 v[10:11], v[142:143], s[86:87], v[10:11] op_sel_hi:[1,0,1]
	v_lshl_add_u64 v[134:135], v[134:135], 0, v[162:163]
	s_waitcnt vmcnt(0)
	v_mov_b64_e32 v[134:135], v[224:225]
	v_mov_b64_e32 v[136:137], v[226:227]
	v_lshl_add_u64 v[138:139], s[88:89], 0, v[138:139]
	v_lshl_add_u64 v[142:143], v[138:139], 0, v[164:165]
	s_waitcnt vmcnt(0)
	v_mov_b64_e32 v[138:139], v[228:229]
	v_mov_b64_e32 v[140:141], v[230:231]
	v_mov_b32_e32 v173, v8
	v_mov_b32_e32 v174, v6
	v_mov_b32_e32 v175, v9
	v_mov_b32_e32 v176, v2
	v_mov_b32_e32 v177, v5
	v_add_f32_e32 v197, v16, v17
	v_mov_b32_e32 v196, v11
	s_waitcnt vmcnt(1)
	v_cvt_pk_f32_fp8_sdwa v[146:147], v134 src0_sel:WORD_1
	v_cvt_pk_f32_fp8_e32 v[144:145], v134
	v_cvt_pk_f32_fp8_e32 v[148:149], v135
	v_cvt_pk_f32_fp8_sdwa v[134:135], v135 src0_sel:WORD_1
	s_waitcnt vmcnt(0)
	v_lshlrev_b32_e32 v150, 16, v138
	v_and_b32_e32 v151, 0xffff0000, v138
	v_lshlrev_b32_e32 v138, 16, v139
	v_and_b32_e32 v139, 0xffff0000, v139
	v_pk_fma_f32 v[138:139], v[146:147], s[4:5], v[138:139] op_sel_hi:[1,0,1]
	v_lshlrev_b32_e32 v146, 16, v140
	v_and_b32_e32 v147, 0xffff0000, v140
	v_lshlrev_b32_e32 v140, 16, v141
	v_and_b32_e32 v141, 0xffff0000, v141
	v_pk_fma_f32 v[134:135], v[134:135], s[4:5], v[140:141] op_sel_hi:[1,0,1]
	v_pk_fma_f32 v[32:33], v[138:139], s[86:87], v[32:33] op_sel_hi:[1,0,1]
	s_waitcnt vmcnt(0)
	v_mov_b64_e32 v[138:139], v[232:233]
	v_mov_b64_e32 v[140:141], v[234:235]
	v_pk_fma_f32 v[28:29], v[134:135], s[86:87], v[28:29] op_sel_hi:[1,0,1]
	v_cvt_pk_f32_fp8_e32 v[134:135], v136
	v_pk_fma_f32 v[146:147], v[148:149], s[4:5], v[146:147] op_sel_hi:[1,0,1]
	v_cvt_pk_f32_fp8_sdwa v[142:143], v136 src0_sel:WORD_1
	v_pk_fma_f32 v[144:145], v[144:145], s[4:5], v[150:151] op_sel_hi:[1,0,1]
	v_pk_fma_f32 v[26:27], v[146:147], s[86:87], v[26:27] op_sel_hi:[1,0,1]
	v_pk_fma_f32 v[30:31], v[144:145], s[86:87], v[30:31] op_sel_hi:[1,0,1]
	v_cvt_pk_f32_fp8_e32 v[144:145], v137
	v_cvt_pk_f32_fp8_sdwa v[136:137], v137 src0_sel:WORD_1
	s_waitcnt vmcnt(0)
	v_lshlrev_b32_e32 v146, 16, v138
	v_and_b32_e32 v147, 0xffff0000, v138
	v_pk_fma_f32 v[134:135], v[134:135], s[4:5], v[146:147] op_sel_hi:[1,0,1]
	v_lshlrev_b32_e32 v138, 16, v139
	v_and_b32_e32 v139, 0xffff0000, v139
	v_pk_fma_f32 v[46:47], v[134:135], s[86:87], v[46:47] op_sel_hi:[1,0,1]
	v_or_b32_e32 v134, 32, v132
	v_pk_fma_f32 v[138:139], v[142:143], s[4:5], v[138:139] op_sel_hi:[1,0,1]
	v_ashrrev_i32_e32 v135, 31, v134
	v_lshlrev_b32_e32 v142, 16, v140
	v_and_b32_e32 v143, 0xffff0000, v140
	v_lshlrev_b32_e32 v140, 16, v141
	v_and_b32_e32 v141, 0xffff0000, v141
	v_pk_fma_f32 v[48:49], v[138:139], s[86:87], v[48:49] op_sel_hi:[1,0,1]
	v_lshlrev_b64 v[138:139], 11, v[134:135]
	v_pk_fma_f32 v[142:143], v[144:145], s[4:5], v[142:143] op_sel_hi:[1,0,1]
	v_pk_fma_f32 v[136:137], v[136:137], s[4:5], v[140:141] op_sel_hi:[1,0,1]
	v_lshl_add_u64 v[134:135], s[92:93], 0, v[138:139]
	v_pk_fma_f32 v[44:45], v[136:137], s[86:87], v[44:45] op_sel_hi:[1,0,1]
	v_pk_fma_f32 v[42:43], v[142:143], s[86:87], v[42:43] op_sel_hi:[1,0,1]
	v_lshl_add_u64 v[134:135], v[134:135], 0, v[162:163]
	s_waitcnt vmcnt(0)
	v_mov_b64_e32 v[134:135], v[236:237]
	v_mov_b64_e32 v[136:137], v[238:239]
	v_lshl_add_u64 v[138:139], s[88:89], 0, v[138:139]
	v_lshl_add_u64 v[142:143], v[138:139], 0, v[164:165]
	s_waitcnt vmcnt(0)
	v_mov_b64_e32 v[138:139], v[240:241]
	v_mov_b64_e32 v[140:141], v[242:243]
	s_waitcnt vmcnt(1)
	v_cvt_pk_f32_fp8_sdwa v[146:147], v134 src0_sel:WORD_1
	v_cvt_pk_f32_fp8_e32 v[144:145], v134
	v_cvt_pk_f32_fp8_e32 v[148:149], v135
	v_cvt_pk_f32_fp8_sdwa v[134:135], v135 src0_sel:WORD_1
	s_waitcnt vmcnt(0)
	v_lshlrev_b32_e32 v150, 16, v138
	v_and_b32_e32 v151, 0xffff0000, v138
	v_lshlrev_b32_e32 v138, 16, v139
	v_and_b32_e32 v139, 0xffff0000, v139
	v_pk_fma_f32 v[138:139], v[146:147], s[4:5], v[138:139] op_sel_hi:[1,0,1]
	v_lshlrev_b32_e32 v146, 16, v140
	v_and_b32_e32 v147, 0xffff0000, v140
	v_lshlrev_b32_e32 v140, 16, v141
	v_and_b32_e32 v141, 0xffff0000, v141
	v_pk_fma_f32 v[134:135], v[134:135], s[4:5], v[140:141] op_sel_hi:[1,0,1]
	v_pk_fma_f32 v[60:61], v[138:139], s[86:87], v[60:61] op_sel_hi:[1,0,1]
	s_waitcnt vmcnt(0)
	v_mov_b64_e32 v[138:139], v[244:245]
	v_mov_b64_e32 v[140:141], v[246:247]
	s_mov_b32 s98, 0x18000
	s_mov_b32 s99, 0
	v_lshl_add_u64 v[212:213], v[248:249], 0, s[98:99]
	global_load_dwordx4 v[212:215], v[212:213], off
	s_mov_b32 s98, 0x18000
	s_mov_b32 s99, 0
	v_lshl_add_u64 v[216:217], v[250:251], 0, s[98:99]
	global_load_dwordx4 v[216:219], v[216:217], off
	s_mov_b32 s98, 0x18000
	s_mov_b32 s99, 0
	v_lshl_add_u64 v[220:221], v[250:251], 0, s[98:99]
	global_load_dwordx4 v[220:223], v[220:221], off offset:256
	s_mov_b32 s98, 0x40000
	s_mov_b32 s99, 0
	v_lshl_add_u64 v[224:225], v[248:249], 0, s[98:99]
	global_load_dwordx4 v[224:227], v[224:225], off
	s_mov_b32 s98, 0x40000
	s_mov_b32 s99, 0
	v_lshl_add_u64 v[228:229], v[250:251], 0, s[98:99]
	global_load_dwordx4 v[228:231], v[228:229], off
	s_mov_b32 s98, 0x40000
	s_mov_b32 s99, 0
	v_lshl_add_u64 v[232:233], v[250:251], 0, s[98:99]
	global_load_dwordx4 v[232:235], v[232:233], off offset:256
	s_mov_b32 s98, 0x48000
	s_mov_b32 s99, 0
	v_lshl_add_u64 v[236:237], v[248:249], 0, s[98:99]
	global_load_dwordx4 v[236:239], v[236:237], off
	s_mov_b32 s98, 0x48000
	s_mov_b32 s99, 0
	v_lshl_add_u64 v[240:241], v[250:251], 0, s[98:99]
	global_load_dwordx4 v[240:243], v[240:241], off
	s_mov_b32 s98, 0x48000
	s_mov_b32 s99, 0
	v_lshl_add_u64 v[244:245], v[250:251], 0, s[98:99]
	global_load_dwordx4 v[244:247], v[244:245], off offset:256
	v_pk_fma_f32 v[52:53], v[134:135], s[86:87], v[52:53] op_sel_hi:[1,0,1]
	v_cvt_pk_f32_fp8_e32 v[134:135], v136
	v_pk_fma_f32 v[146:147], v[148:149], s[4:5], v[146:147] op_sel_hi:[1,0,1]
	v_cvt_pk_f32_fp8_sdwa v[142:143], v136 src0_sel:WORD_1
	v_pk_fma_f32 v[144:145], v[144:145], s[4:5], v[150:151] op_sel_hi:[1,0,1]
	v_pk_fma_f32 v[50:51], v[146:147], s[86:87], v[50:51] op_sel_hi:[1,0,1]
	v_pk_fma_f32 v[58:59], v[144:145], s[86:87], v[58:59] op_sel_hi:[1,0,1]
	v_cvt_pk_f32_fp8_e32 v[144:145], v137
	v_cvt_pk_f32_fp8_sdwa v[136:137], v137 src0_sel:WORD_1
	s_waitcnt vmcnt(0)
	v_lshlrev_b32_e32 v146, 16, v138
	v_and_b32_e32 v147, 0xffff0000, v138
	v_pk_fma_f32 v[134:135], v[134:135], s[4:5], v[146:147] op_sel_hi:[1,0,1]
	v_lshlrev_b32_e32 v138, 16, v139
	v_and_b32_e32 v139, 0xffff0000, v139
	v_pk_fma_f32 v[70:71], v[134:135], s[86:87], v[70:71] op_sel_hi:[1,0,1]
	v_or_b32_e32 v134, 48, v132
	v_pk_fma_f32 v[138:139], v[142:143], s[4:5], v[138:139] op_sel_hi:[1,0,1]
	v_ashrrev_i32_e32 v135, 31, v134
	v_lshlrev_b32_e32 v142, 16, v140
	v_and_b32_e32 v143, 0xffff0000, v140
	v_lshlrev_b32_e32 v140, 16, v141
	v_and_b32_e32 v141, 0xffff0000, v141
	v_pk_fma_f32 v[72:73], v[138:139], s[86:87], v[72:73] op_sel_hi:[1,0,1]
	v_lshlrev_b64 v[138:139], 11, v[134:135]
	v_pk_fma_f32 v[142:143], v[144:145], s[4:5], v[142:143] op_sel_hi:[1,0,1]
	v_pk_fma_f32 v[136:137], v[136:137], s[4:5], v[140:141] op_sel_hi:[1,0,1]
	v_lshl_add_u64 v[134:135], s[92:93], 0, v[138:139]
	v_pk_fma_f32 v[68:69], v[136:137], s[86:87], v[68:69] op_sel_hi:[1,0,1]
	v_pk_fma_f32 v[66:67], v[142:143], s[86:87], v[66:67] op_sel_hi:[1,0,1]
	v_lshl_add_u64 v[134:135], v[134:135], 0, v[162:163]
	s_waitcnt vmcnt(0)
	v_mov_b64_e32 v[134:135], v[212:213]
	v_mov_b64_e32 v[136:137], v[214:215]
	v_lshl_add_u64 v[138:139], s[88:89], 0, v[138:139]
	v_lshl_add_u64 v[142:143], v[138:139], 0, v[164:165]
	s_waitcnt vmcnt(0)
	v_mov_b64_e32 v[138:139], v[216:217]
	v_mov_b64_e32 v[140:141], v[218:219]
	s_waitcnt vmcnt(1)
	v_cvt_pk_f32_fp8_sdwa v[146:147], v134 src0_sel:WORD_1
	v_cvt_pk_f32_fp8_e32 v[144:145], v134
	v_cvt_pk_f32_fp8_e32 v[148:149], v135
	v_cvt_pk_f32_fp8_sdwa v[134:135], v135 src0_sel:WORD_1
	s_waitcnt vmcnt(0)
	v_lshlrev_b32_e32 v150, 16, v138
	v_and_b32_e32 v151, 0xffff0000, v138
	v_lshlrev_b32_e32 v138, 16, v139
	v_and_b32_e32 v139, 0xffff0000, v139
	v_pk_fma_f32 v[138:139], v[146:147], s[4:5], v[138:139] op_sel_hi:[1,0,1]
	v_lshlrev_b32_e32 v146, 16, v140
	v_and_b32_e32 v147, 0xffff0000, v140
	v_lshlrev_b32_e32 v140, 16, v141
	v_and_b32_e32 v141, 0xffff0000, v141
	v_pk_fma_f32 v[134:135], v[134:135], s[4:5], v[140:141] op_sel_hi:[1,0,1]
	v_pk_fma_f32 v[88:89], v[138:139], s[86:87], v[88:89] op_sel_hi:[1,0,1]
	s_waitcnt vmcnt(0)
	v_mov_b64_e32 v[138:139], v[220:221]
	v_mov_b64_e32 v[140:141], v[222:223]
	v_pk_fma_f32 v[84:85], v[134:135], s[86:87], v[84:85] op_sel_hi:[1,0,1]
	v_cvt_pk_f32_fp8_e32 v[134:135], v136
	v_pk_fma_f32 v[146:147], v[148:149], s[4:5], v[146:147] op_sel_hi:[1,0,1]
	v_cvt_pk_f32_fp8_sdwa v[142:143], v136 src0_sel:WORD_1
	v_pk_fma_f32 v[144:145], v[144:145], s[4:5], v[150:151] op_sel_hi:[1,0,1]
	v_pk_fma_f32 v[82:83], v[146:147], s[86:87], v[82:83] op_sel_hi:[1,0,1]
	v_pk_fma_f32 v[86:87], v[144:145], s[86:87], v[86:87] op_sel_hi:[1,0,1]
	v_cvt_pk_f32_fp8_e32 v[144:145], v137
	v_cvt_pk_f32_fp8_sdwa v[136:137], v137 src0_sel:WORD_1
	s_waitcnt vmcnt(0)
	v_lshlrev_b32_e32 v146, 16, v138
	v_and_b32_e32 v147, 0xffff0000, v138
	v_pk_fma_f32 v[134:135], v[134:135], s[4:5], v[146:147] op_sel_hi:[1,0,1]
	v_lshlrev_b32_e32 v138, 16, v139
	v_and_b32_e32 v139, 0xffff0000, v139
	v_pk_fma_f32 v[94:95], v[134:135], s[86:87], v[94:95] op_sel_hi:[1,0,1]
	v_add_u32_e32 v134, 0x80, v132
	v_pk_fma_f32 v[138:139], v[142:143], s[4:5], v[138:139] op_sel_hi:[1,0,1]
	v_ashrrev_i32_e32 v135, 31, v134
	v_lshlrev_b32_e32 v142, 16, v140
	v_and_b32_e32 v143, 0xffff0000, v140
	v_lshlrev_b32_e32 v140, 16, v141
	v_and_b32_e32 v141, 0xffff0000, v141
	v_pk_fma_f32 v[96:97], v[138:139], s[86:87], v[96:97] op_sel_hi:[1,0,1]
	v_lshlrev_b64 v[138:139], 11, v[134:135]
	v_pk_fma_f32 v[142:143], v[144:145], s[4:5], v[142:143] op_sel_hi:[1,0,1]
	v_pk_fma_f32 v[136:137], v[136:137], s[4:5], v[140:141] op_sel_hi:[1,0,1]
	v_lshl_add_u64 v[134:135], s[92:93], 0, v[138:139]
	v_pk_fma_f32 v[92:93], v[136:137], s[86:87], v[92:93] op_sel_hi:[1,0,1]
	v_pk_fma_f32 v[90:91], v[142:143], s[86:87], v[90:91] op_sel_hi:[1,0,1]
	v_lshl_add_u64 v[134:135], v[134:135], 0, v[162:163]
	s_waitcnt vmcnt(0)
	v_mov_b64_e32 v[134:135], v[224:225]
	v_mov_b64_e32 v[136:137], v[226:227]
	v_lshl_add_u64 v[138:139], s[88:89], 0, v[138:139]
	v_lshl_add_u64 v[142:143], v[138:139], 0, v[164:165]
	s_waitcnt vmcnt(0)
	v_mov_b64_e32 v[138:139], v[228:229]
	v_mov_b64_e32 v[140:141], v[230:231]
	s_waitcnt vmcnt(1)
	v_cvt_pk_f32_fp8_sdwa v[146:147], v134 src0_sel:WORD_1
	v_cvt_pk_f32_fp8_e32 v[144:145], v134
	v_cvt_pk_f32_fp8_e32 v[148:149], v135
	v_cvt_pk_f32_fp8_sdwa v[134:135], v135 src0_sel:WORD_1
	s_waitcnt vmcnt(0)
	v_lshlrev_b32_e32 v150, 16, v138
	v_and_b32_e32 v151, 0xffff0000, v138
	v_lshlrev_b32_e32 v138, 16, v139
	v_and_b32_e32 v139, 0xffff0000, v139
	v_pk_fma_f32 v[138:139], v[146:147], s[4:5], v[138:139] op_sel_hi:[1,0,1]
	v_lshlrev_b32_e32 v146, 16, v140
	v_and_b32_e32 v147, 0xffff0000, v140
	v_lshlrev_b32_e32 v140, 16, v141
	v_and_b32_e32 v141, 0xffff0000, v141
	v_pk_fma_f32 v[134:135], v[134:135], s[4:5], v[140:141] op_sel_hi:[1,0,1]
	v_pk_fma_f32 v[112:113], v[138:139], s[86:87], v[112:113] op_sel_hi:[1,0,1]
	s_waitcnt vmcnt(0)
	v_mov_b64_e32 v[138:139], v[232:233]
	v_mov_b64_e32 v[140:141], v[234:235]
	v_pk_fma_f32 v[108:109], v[134:135], s[86:87], v[108:109] op_sel_hi:[1,0,1]
	v_cvt_pk_f32_fp8_e32 v[134:135], v136
	v_pk_fma_f32 v[146:147], v[148:149], s[4:5], v[146:147] op_sel_hi:[1,0,1]
	v_cvt_pk_f32_fp8_sdwa v[142:143], v136 src0_sel:WORD_1
	v_pk_fma_f32 v[144:145], v[144:145], s[4:5], v[150:151] op_sel_hi:[1,0,1]
	v_pk_fma_f32 v[106:107], v[146:147], s[86:87], v[106:107] op_sel_hi:[1,0,1]
	v_pk_fma_f32 v[110:111], v[144:145], s[86:87], v[110:111] op_sel_hi:[1,0,1]
	v_cvt_pk_f32_fp8_e32 v[144:145], v137
	v_cvt_pk_f32_fp8_sdwa v[136:137], v137 src0_sel:WORD_1
	s_waitcnt vmcnt(0)
	v_lshlrev_b32_e32 v146, 16, v138
	v_and_b32_e32 v147, 0xffff0000, v138
	v_pk_fma_f32 v[134:135], v[134:135], s[4:5], v[146:147] op_sel_hi:[1,0,1]
	v_lshlrev_b32_e32 v138, 16, v139
	v_and_b32_e32 v139, 0xffff0000, v139
	v_pk_fma_f32 v[118:119], v[134:135], s[86:87], v[118:119] op_sel_hi:[1,0,1]
	v_add_u32_e32 v134, 0x90, v132
	v_pk_fma_f32 v[138:139], v[142:143], s[4:5], v[138:139] op_sel_hi:[1,0,1]
	v_ashrrev_i32_e32 v135, 31, v134
	v_lshlrev_b32_e32 v142, 16, v140
	v_and_b32_e32 v143, 0xffff0000, v140
	v_lshlrev_b32_e32 v140, 16, v141
	v_and_b32_e32 v141, 0xffff0000, v141
	v_pk_fma_f32 v[120:121], v[138:139], s[86:87], v[120:121] op_sel_hi:[1,0,1]
	v_lshlrev_b64 v[138:139], 11, v[134:135]
	v_pk_fma_f32 v[142:143], v[144:145], s[4:5], v[142:143] op_sel_hi:[1,0,1]
	v_pk_fma_f32 v[136:137], v[136:137], s[4:5], v[140:141] op_sel_hi:[1,0,1]
	v_lshl_add_u64 v[134:135], s[92:93], 0, v[138:139]
	v_pk_fma_f32 v[116:117], v[136:137], s[86:87], v[116:117] op_sel_hi:[1,0,1]
	v_pk_fma_f32 v[114:115], v[142:143], s[86:87], v[114:115] op_sel_hi:[1,0,1]
	v_lshl_add_u64 v[134:135], v[134:135], 0, v[162:163]
	s_waitcnt vmcnt(0)
	v_mov_b64_e32 v[134:135], v[236:237]
	v_mov_b64_e32 v[136:137], v[238:239]
	v_lshl_add_u64 v[138:139], s[88:89], 0, v[138:139]
	v_lshl_add_u64 v[142:143], v[138:139], 0, v[164:165]
	s_waitcnt vmcnt(0)
	v_mov_b64_e32 v[138:139], v[240:241]
	v_mov_b64_e32 v[140:141], v[242:243]
	s_waitcnt vmcnt(1)
	v_cvt_pk_f32_fp8_sdwa v[146:147], v134 src0_sel:WORD_1
	v_cvt_pk_f32_fp8_e32 v[144:145], v134
	v_cvt_pk_f32_fp8_e32 v[148:149], v135
	v_cvt_pk_f32_fp8_sdwa v[134:135], v135 src0_sel:WORD_1
	s_waitcnt vmcnt(0)
	v_lshlrev_b32_e32 v150, 16, v138
	v_and_b32_e32 v151, 0xffff0000, v138
	v_lshlrev_b32_e32 v138, 16, v139
	v_and_b32_e32 v139, 0xffff0000, v139
	v_pk_fma_f32 v[138:139], v[146:147], s[4:5], v[138:139] op_sel_hi:[1,0,1]
	v_lshlrev_b32_e32 v146, 16, v140
	v_and_b32_e32 v147, 0xffff0000, v140
	v_lshlrev_b32_e32 v140, 16, v141
	v_and_b32_e32 v141, 0xffff0000, v141
	v_pk_fma_f32 v[134:135], v[134:135], s[4:5], v[140:141] op_sel_hi:[1,0,1]
	v_pk_fma_f32 v[128:129], v[138:139], s[86:87], v[128:129] op_sel_hi:[1,0,1]
	s_waitcnt vmcnt(0)
	v_mov_b64_e32 v[138:139], v[244:245]
	v_mov_b64_e32 v[140:141], v[246:247]
	s_mov_b32 s98, 0x50000
	s_mov_b32 s99, 0
	v_lshl_add_u64 v[212:213], v[248:249], 0, s[98:99]
	global_load_dwordx4 v[212:215], v[212:213], off
	s_mov_b32 s98, 0x50000
	s_mov_b32 s99, 0
	v_lshl_add_u64 v[216:217], v[250:251], 0, s[98:99]
	global_load_dwordx4 v[216:219], v[216:217], off
	s_mov_b32 s98, 0x50000
	s_mov_b32 s99, 0
	v_lshl_add_u64 v[220:221], v[250:251], 0, s[98:99]
	global_load_dwordx4 v[220:223], v[220:221], off offset:256
	s_mov_b32 s98, 0x58000
	s_mov_b32 s99, 0
	v_lshl_add_u64 v[224:225], v[248:249], 0, s[98:99]
	global_load_dwordx4 v[224:227], v[224:225], off
	s_mov_b32 s98, 0x58000
	s_mov_b32 s99, 0
	v_lshl_add_u64 v[228:229], v[250:251], 0, s[98:99]
	global_load_dwordx4 v[228:231], v[228:229], off
	s_mov_b32 s98, 0x58000
	s_mov_b32 s99, 0
	v_lshl_add_u64 v[232:233], v[250:251], 0, s[98:99]
	global_load_dwordx4 v[232:235], v[232:233], off offset:256
	v_pk_fma_f32 v[124:125], v[134:135], s[86:87], v[124:125] op_sel_hi:[1,0,1]
	v_cvt_pk_f32_fp8_e32 v[134:135], v136
	v_pk_fma_f32 v[146:147], v[148:149], s[4:5], v[146:147] op_sel_hi:[1,0,1]
	v_cvt_pk_f32_fp8_sdwa v[142:143], v136 src0_sel:WORD_1
	v_pk_fma_f32 v[144:145], v[144:145], s[4:5], v[150:151] op_sel_hi:[1,0,1]
	v_pk_fma_f32 v[122:123], v[146:147], s[86:87], v[122:123] op_sel_hi:[1,0,1]
	v_pk_fma_f32 v[126:127], v[144:145], s[86:87], v[126:127] op_sel_hi:[1,0,1]
	v_cvt_pk_f32_fp8_e32 v[144:145], v137
	v_cvt_pk_f32_fp8_sdwa v[136:137], v137 src0_sel:WORD_1
	s_waitcnt vmcnt(0)
	v_lshlrev_b32_e32 v146, 16, v138
	v_and_b32_e32 v147, 0xffff0000, v138
	v_pk_fma_f32 v[134:135], v[134:135], s[4:5], v[146:147] op_sel_hi:[1,0,1]
	v_lshlrev_b32_e32 v138, 16, v139
	v_and_b32_e32 v139, 0xffff0000, v139
	v_pk_fma_f32 v[102:103], v[134:135], s[86:87], v[102:103] op_sel_hi:[1,0,1]
	v_add_u32_e32 v134, 0xa0, v132
	v_pk_fma_f32 v[138:139], v[142:143], s[4:5], v[138:139] op_sel_hi:[1,0,1]
	v_ashrrev_i32_e32 v135, 31, v134
	v_lshlrev_b32_e32 v142, 16, v140
	v_and_b32_e32 v143, 0xffff0000, v140
	v_lshlrev_b32_e32 v140, 16, v141
	v_and_b32_e32 v141, 0xffff0000, v141
	v_pk_fma_f32 v[104:105], v[138:139], s[86:87], v[104:105] op_sel_hi:[1,0,1]
	v_lshlrev_b64 v[138:139], 11, v[134:135]
	v_pk_fma_f32 v[142:143], v[144:145], s[4:5], v[142:143] op_sel_hi:[1,0,1]
	v_pk_fma_f32 v[136:137], v[136:137], s[4:5], v[140:141] op_sel_hi:[1,0,1]
	v_lshl_add_u64 v[134:135], s[92:93], 0, v[138:139]
	v_pk_fma_f32 v[100:101], v[136:137], s[86:87], v[100:101] op_sel_hi:[1,0,1]
	v_pk_fma_f32 v[98:99], v[142:143], s[86:87], v[98:99] op_sel_hi:[1,0,1]
	v_lshl_add_u64 v[134:135], v[134:135], 0, v[162:163]
	s_waitcnt vmcnt(0)
	v_mov_b64_e32 v[134:135], v[212:213]
	v_mov_b64_e32 v[136:137], v[214:215]
	v_lshl_add_u64 v[138:139], s[88:89], 0, v[138:139]
	v_lshl_add_u64 v[142:143], v[138:139], 0, v[164:165]
	s_waitcnt vmcnt(0)
	v_mov_b64_e32 v[138:139], v[216:217]
	v_mov_b64_e32 v[140:141], v[218:219]
	v_add_u32_e32 v132, 0xb0, v132
	v_ashrrev_i32_e32 v133, 31, v132
	s_waitcnt vmcnt(1)
	v_cvt_pk_f32_fp8_sdwa v[146:147], v134 src0_sel:WORD_1
	v_cvt_pk_f32_fp8_e32 v[144:145], v134
	v_cvt_pk_f32_fp8_e32 v[148:149], v135
	v_cvt_pk_f32_fp8_sdwa v[134:135], v135 src0_sel:WORD_1
	s_waitcnt vmcnt(0)
	v_lshlrev_b32_e32 v150, 16, v138
	v_and_b32_e32 v151, 0xffff0000, v138
	v_lshlrev_b32_e32 v138, 16, v139
	v_and_b32_e32 v139, 0xffff0000, v139
	v_pk_fma_f32 v[138:139], v[146:147], s[4:5], v[138:139] op_sel_hi:[1,0,1]
	v_lshlrev_b32_e32 v146, 16, v140
	v_and_b32_e32 v147, 0xffff0000, v140
	v_lshlrev_b32_e32 v140, 16, v141
	v_and_b32_e32 v141, 0xffff0000, v141
	v_pk_fma_f32 v[134:135], v[134:135], s[4:5], v[140:141] op_sel_hi:[1,0,1]
	v_pk_fma_f32 v[80:81], v[138:139], s[86:87], v[80:81] op_sel_hi:[1,0,1]
	s_waitcnt vmcnt(0)
	v_mov_b64_e32 v[138:139], v[220:221]
	v_mov_b64_e32 v[140:141], v[222:223]
	v_pk_fma_f32 v[144:145], v[144:145], s[4:5], v[150:151] op_sel_hi:[1,0,1]
	v_cvt_pk_f32_fp8_sdwa v[142:143], v136 src0_sel:WORD_1
	v_pk_fma_f32 v[78:79], v[144:145], s[86:87], v[78:79] op_sel_hi:[1,0,1]
	v_pk_fma_f32 v[76:77], v[134:135], s[86:87], v[76:77] op_sel_hi:[1,0,1]
	v_cvt_pk_f32_fp8_e32 v[134:135], v136
	v_cvt_pk_f32_fp8_e32 v[144:145], v137
	v_cvt_pk_f32_fp8_sdwa v[136:137], v137 src0_sel:WORD_1
	v_pk_fma_f32 v[146:147], v[148:149], s[4:5], v[146:147] op_sel_hi:[1,0,1]
	s_nop 0
	v_pk_fma_f32 v[74:75], v[146:147], s[86:87], v[74:75] op_sel_hi:[1,0,1]
	s_waitcnt vmcnt(0)
	v_lshlrev_b32_e32 v146, 16, v138
	v_and_b32_e32 v147, 0xffff0000, v138
	v_lshlrev_b32_e32 v138, 16, v139
	v_and_b32_e32 v139, 0xffff0000, v139
	v_pk_fma_f32 v[138:139], v[142:143], s[4:5], v[138:139] op_sel_hi:[1,0,1]
	v_lshlrev_b32_e32 v142, 16, v140
	v_and_b32_e32 v143, 0xffff0000, v140
	v_lshlrev_b32_e32 v140, 16, v141
	v_and_b32_e32 v141, 0xffff0000, v141
	v_pk_fma_f32 v[136:137], v[136:137], s[4:5], v[140:141] op_sel_hi:[1,0,1]
	v_pk_fma_f32 v[134:135], v[134:135], s[4:5], v[146:147] op_sel_hi:[1,0,1]
	v_pk_fma_f32 v[56:57], v[136:137], s[86:87], v[56:57] op_sel_hi:[1,0,1]
	v_lshlrev_b64 v[136:137], 11, v[132:133]
	v_pk_fma_f32 v[142:143], v[144:145], s[4:5], v[142:143] op_sel_hi:[1,0,1]
	v_lshl_add_u64 v[132:133], s[92:93], 0, v[136:137]
	v_pk_fma_f32 v[64:65], v[138:139], s[86:87], v[64:65] op_sel_hi:[1,0,1]
	v_pk_fma_f32 v[62:63], v[134:135], s[86:87], v[62:63] op_sel_hi:[1,0,1]
	v_pk_fma_f32 v[54:55], v[142:143], s[86:87], v[54:55] op_sel_hi:[1,0,1]
	v_lshl_add_u64 v[132:133], v[132:133], 0, v[162:163]
	s_waitcnt vmcnt(0)
	v_mov_b64_e32 v[132:133], v[224:225]
	v_mov_b64_e32 v[134:135], v[226:227]
	v_lshl_add_u64 v[136:137], s[88:89], 0, v[136:137]
	v_lshl_add_u64 v[140:141], v[136:137], 0, v[164:165]
	s_waitcnt vmcnt(0)
	v_mov_b64_e32 v[136:137], v[228:229]
	v_mov_b64_e32 v[138:139], v[230:231]
	s_waitcnt vmcnt(1)
	v_cvt_pk_f32_fp8_sdwa v[144:145], v132 src0_sel:WORD_1
	v_cvt_pk_f32_fp8_e32 v[142:143], v132
	v_cvt_pk_f32_fp8_e32 v[146:147], v133
	v_cvt_pk_f32_fp8_sdwa v[132:133], v133 src0_sel:WORD_1
	s_waitcnt vmcnt(0)
	v_lshlrev_b32_e32 v148, 16, v136
	v_and_b32_e32 v149, 0xffff0000, v136
	v_lshlrev_b32_e32 v136, 16, v137
	v_and_b32_e32 v137, 0xffff0000, v137
	v_pk_fma_f32 v[136:137], v[144:145], s[4:5], v[136:137] op_sel_hi:[1,0,1]
	v_lshlrev_b32_e32 v144, 16, v138
	v_and_b32_e32 v145, 0xffff0000, v138
	v_lshlrev_b32_e32 v138, 16, v139
	v_and_b32_e32 v139, 0xffff0000, v139
	v_pk_fma_f32 v[132:133], v[132:133], s[4:5], v[138:139] op_sel_hi:[1,0,1]
	v_pk_fma_f32 v[40:41], v[136:137], s[86:87], v[40:41] op_sel_hi:[1,0,1]
	s_waitcnt vmcnt(0)
	v_mov_b64_e32 v[136:137], v[232:233]
	v_mov_b64_e32 v[138:139], v[234:235]
	v_pk_fma_f32 v[142:143], v[142:143], s[4:5], v[148:149] op_sel_hi:[1,0,1]
	v_cvt_pk_f32_fp8_sdwa v[140:141], v134 src0_sel:WORD_1
	v_pk_fma_f32 v[38:39], v[142:143], s[86:87], v[38:39] op_sel_hi:[1,0,1]
	v_pk_fma_f32 v[36:37], v[132:133], s[86:87], v[36:37] op_sel_hi:[1,0,1]
	v_cvt_pk_f32_fp8_e32 v[132:133], v134
	v_cvt_pk_f32_fp8_e32 v[142:143], v135
	v_cvt_pk_f32_fp8_sdwa v[134:135], v135 src0_sel:WORD_1
	v_pk_fma_f32 v[144:145], v[146:147], s[4:5], v[144:145] op_sel_hi:[1,0,1]
	s_nop 0
	v_pk_fma_f32 v[34:35], v[144:145], s[86:87], v[34:35] op_sel_hi:[1,0,1]
	s_waitcnt vmcnt(0)
	v_lshlrev_b32_e32 v144, 16, v136
	v_and_b32_e32 v145, 0xffff0000, v136
	v_lshlrev_b32_e32 v136, 16, v137
	v_and_b32_e32 v137, 0xffff0000, v137
	v_pk_fma_f32 v[136:137], v[140:141], s[4:5], v[136:137] op_sel_hi:[1,0,1]
	v_lshlrev_b32_e32 v140, 16, v138
	v_and_b32_e32 v141, 0xffff0000, v138
	v_lshlrev_b32_e32 v138, 16, v139
	v_and_b32_e32 v139, 0xffff0000, v139
	v_pk_fma_f32 v[132:133], v[132:133], s[4:5], v[144:145] op_sel_hi:[1,0,1]
	v_pk_fma_f32 v[140:141], v[142:143], s[4:5], v[140:141] op_sel_hi:[1,0,1]
	v_pk_fma_f32 v[134:135], v[134:135], s[4:5], v[138:139] op_sel_hi:[1,0,1]
	v_readlane_b32 s4, v255, 18
	v_readlane_b32 s5, v255, 19
	v_pk_fma_f32 v[22:23], v[132:133], s[86:87], v[22:23] op_sel_hi:[1,0,1]
	v_pk_fma_f32 v[20:21], v[134:135], s[86:87], v[20:21] op_sel_hi:[1,0,1]
	v_lshl_add_u64 v[132:133], s[4:5], 0, v[130:131]
	s_mov_b64 s[4:5], 0x1000
	v_lshl_add_u64 v[130:131], s[6:7], 0, v[130:131]
	v_lshl_add_u64 v[134:135], v[132:133], 0, s[4:5]
	v_lshl_add_u64 v[142:143], v[130:131], 0, s[4:5]
	s_movk_i32 s4, 0x1000
	v_add_co_u32_e32 v132, vcc, s4, v132
	v_pk_fma_f32 v[24:25], v[136:137], s[86:87], v[24:25] op_sel_hi:[1,0,1]
	s_nop 0
	v_addc_co_u32_e32 v133, vcc, 0, v133, vcc
	v_add_co_u32_e32 v130, vcc, s4, v130
	v_pk_fma_f32 v[18:19], v[140:141], s[86:87], v[18:19] op_sel_hi:[1,0,1]
	s_nop 0
	v_addc_co_u32_e32 v131, vcc, 0, v131, vcc
	global_load_dwordx4 v[154:157], v[132:133], off
	global_load_dwordx4 v[146:149], v[134:135], off offset:16
	global_load_dwordx4 v[158:161], v[130:131], off
	global_load_dwordx4 v[150:153], v[142:143], off offset:16
	s_nop 0
	global_load_dwordx4 v[130:133], v[134:135], off offset:528
	global_load_dwordx4 v[138:141], v[134:135], off offset:512
	s_nop 0
	global_load_dwordx4 v[134:137], v[142:143], off offset:528
	s_nop 0
	global_load_dwordx4 v[142:145], v[142:143], off offset:512
	v_cmp_lt_i32_e32 vcc, v170, v171
	s_nop 1
	v_cndmask_b32_e32 v170, v205, v170, vcc
	v_cmp_lt_i32_e32 vcc, v172, v171
	v_lshlrev_b32_e32 v170, 2, v170
	s_nop 0
	v_cndmask_b32_e32 v171, v205, v172, vcc
	v_mov_b32_e32 v172, v7
	v_pk_add_f32 v[172:173], v[172:173], v[174:175]
	v_mov_b32_e32 v174, v3
	v_mov_b32_e32 v175, v4
	v_pk_add_f32 v[174:175], v[174:175], v[176:177]
	v_add_f32_e32 v172, v172, v173
	v_pk_add_f32 v[174:175], v[174:175], v[174:175] op_sel_hi:[0,1]
	v_add_f32_e32 v173, 0, v172
	v_add_f32_e32 v177, v14, v15
	v_mov_b32_e32 v176, v10
	v_mov_b32_e32 v174, v12
	v_mov_b32_e32 v172, v13
	v_pk_add_f32 v[176:177], v[176:177], v[196:197]
	v_pk_add_f32 v[172:173], v[174:175], v[172:173]
	v_lshlrev_b32_e32 v171, 2, v171
	v_pk_add_f32 v[172:173], v[176:177], v[172:173]
	v_cmp_gt_u32_e32 vcc, 16, v169
	v_add_f32_e32 v172, v172, v173
	ds_bpermute_b32 v173, v170, v172
	s_waitcnt lgkmcnt(0)
	v_add_f32_e32 v172, v172, v173
	ds_bpermute_b32 v173, v171, v172
	s_waitcnt lgkmcnt(0)
	v_add_f32_e32 v172, v172, v173
	v_fmamk_f32 v174, v172, 0xbc800000, v9
	v_fmamk_f32 v176, v172, 0xbc800000, v7
	v_fmamk_f32 v173, v172, 0xbc800000, v8
	v_fmamk_f32 v175, v172, 0xbc800000, v6
	v_mul_f32_e32 v176, v176, v176
	v_mul_f32_e32 v174, v174, v174
	v_fmac_f32_e32 v176, v175, v175
	v_fmac_f32_e32 v174, v173, v173
	v_fmamk_f32 v175, v172, 0xbc800000, v5
	v_fmamk_f32 v177, v172, 0xbc800000, v3
	v_add_f32_e32 v173, v176, v174
	v_fmamk_f32 v174, v172, 0xbc800000, v4
	v_fmamk_f32 v176, v172, 0xbc800000, v2
	v_mul_f32_e32 v177, v177, v177
	v_mul_f32_e32 v175, v175, v175
	v_fmac_f32_e32 v177, v176, v176
	v_fmac_f32_e32 v175, v174, v174
	v_add_f32_e32 v174, v177, v175
	v_fmamk_f32 v175, v172, 0xbc800000, v17
	v_fmamk_f32 v177, v172, 0xbc800000, v15
	v_add_f32_e32 v173, v173, v174
	v_fmamk_f32 v174, v172, 0xbc800000, v16
	v_fmamk_f32 v176, v172, 0xbc800000, v14
	v_mul_f32_e32 v177, v177, v177
	v_mul_f32_e32 v175, v175, v175
	v_fmac_f32_e32 v177, v176, v176
	v_fmac_f32_e32 v175, v174, v174
	v_add_f32_e32 v174, v177, v175
	v_fmamk_f32 v175, v172, 0xbc800000, v13
	v_fmamk_f32 v177, v172, 0xbc800000, v11
	v_add_f32_e32 v173, v174, v173
	v_fmamk_f32 v174, v172, 0xbc800000, v12
	v_fmamk_f32 v176, v172, 0xbc800000, v10
	v_mul_f32_e32 v177, v177, v177
	v_mul_f32_e32 v175, v175, v175
	v_fmac_f32_e32 v177, v176, v176
	v_fmac_f32_e32 v175, v174, v174
	v_add_f32_e32 v174, v177, v175
	v_add_f32_e32 v173, v174, v173
	ds_bpermute_b32 v174, v170, v173
	s_waitcnt lgkmcnt(0)
	v_add_f32_e32 v173, v173, v174
	ds_bpermute_b32 v174, v171, v173
	s_and_saveexec_b64 s[4:5], vcc
	v_readlane_b32 s62, v255, 10
	v_readlane_b32 s84, v255, 12
	v_readlane_b32 s28, v255, 14
	v_readlane_b32 s63, v255, 11
	v_readlane_b32 s85, v255, 13
	v_readlane_b32 s29, v255, 15
	s_mov_b32 s94, s67
	s_cbranch_execz .LBB0_1028
	s_lshl_b32 s6, s12, 11
	s_add_i32 s6, s1, s6
	v_mul_f32_e32 v172, 0x3c800000, v172
	v_lshl_add_u32 v175, v167, 5, s6
	s_waitcnt lgkmcnt(0)
	v_add_f32_e32 v173, v173, v174
	ds_write_b64 v175, v[172:173]

.LBB0_1231:
	s_lshl_b64 s[0:1], s[34:35], 2
	s_add_u32 s28, s72, s0
	s_addc_u32 s29, s73, s1
	s_add_u32 s0, s74, s88
	s_addc_u32 s1, s75, s89
	v_lshrrev_b32_e32 v130, 1, v166
	s_add_u32 s34, s0, 0x9c00000
	v_and_b32_e32 v130, 24, v130
	s_addc_u32 s35, s1, 0
	s_lshl_b32 s0, s24, 8
	v_lshl_or_b32 v130, s38, 5, v130
	v_lshl_or_b32 v131, s38, 6, v144
	s_lshl_b32 s88, s93, 8
	v_or_b32_e32 v130, s0, v130
	v_or_b32_e32 v162, s0, v131
	s_add_i32 s0, s88, s84
	v_or_b32_e32 v132, s0, v167
	v_ashrrev_i32_e32 v133, 31, v132
	v_lshlrev_b64 v[138:139], 11, v[132:133]
	v_ashrrev_i32_e32 v163, 31, v162
	v_lshl_add_u64 v[134:135], s[28:29], 0, v[138:139]
	v_lshl_add_u64 v[134:135], v[134:135], 0, v[162:163]
	s_barrier
	v_ashrrev_i32_e32 v131, 31, v130
	v_mov_b64_e32 v[248:249], v[134:135]
	v_lshl_add_u64 v[138:139], s[34:35], 0, v[138:139]
	v_lshlrev_b64 v[164:165], 1, v[130:131]
	v_lshl_add_u64 v[142:143], v[138:139], 0, v[164:165]
	v_mov_b64_e32 v[250:251], v[142:143]
	v_mov_b64_e32 v[212:213], v[248:249]
	global_load_dwordx4 v[212:215], v[212:213], off
	v_mov_b64_e32 v[216:217], v[250:251]
	global_load_dwordx4 v[216:219], v[216:217], off
	v_mov_b64_e32 v[220:221], v[250:251]
	global_load_dwordx4 v[220:223], v[220:221], off offset:256
	s_mov_b32 s98, 0x8000
	s_mov_b32 s99, 0
	v_lshl_add_u64 v[224:225], v[248:249], 0, s[98:99]
	global_load_dwordx4 v[224:227], v[224:225], off
	s_mov_b32 s98, 0x8000
	s_mov_b32 s99, 0
	v_lshl_add_u64 v[228:229], v[250:251], 0, s[98:99]
	global_load_dwordx4 v[228:231], v[228:229], off
	s_mov_b32 s98, 0x8000
	s_mov_b32 s99, 0
	v_lshl_add_u64 v[232:233], v[250:251], 0, s[98:99]
	global_load_dwordx4 v[232:235], v[232:233], off offset:256
	s_mov_b32 s98, 0x10000
	s_mov_b32 s99, 0
	v_lshl_add_u64 v[236:237], v[248:249], 0, s[98:99]
	global_load_dwordx4 v[236:239], v[236:237], off
	s_mov_b32 s98, 0x10000
	s_mov_b32 s99, 0
	v_lshl_add_u64 v[240:241], v[250:251], 0, s[98:99]
	global_load_dwordx4 v[240:243], v[240:241], off
	s_mov_b32 s98, 0x10000
	s_mov_b32 s99, 0
	v_lshl_add_u64 v[244:245], v[250:251], 0, s[98:99]
	global_load_dwordx4 v[244:247], v[244:245], off offset:256
	s_waitcnt vmcnt(0)
	v_mov_b64_e32 v[134:135], v[212:213]
	v_mov_b64_e32 v[136:137], v[214:215]
	v_mov_b64_e32 v[138:139], v[216:217]
	v_mov_b64_e32 v[140:141], v[218:219]
	s_mov_b32 s0, 0x3a000000
	v_readlane_b32 s4, v255, 27
	v_lshlrev_b64 v[130:131], 2, v[130:131]
	v_readlane_b32 s5, v255, 28
	v_and_b32_e32 v171, 64, v205
	v_xor_b32_e32 v170, 16, v205
	v_add_u32_e32 v171, 64, v171
	v_xor_b32_e32 v172, 32, v205
	v_and_b32_e32 v169, 63, v166
	s_waitcnt vmcnt(0)
	v_cvt_pk_f32_fp8_sdwa v[146:147], v134 src0_sel:WORD_1
	v_cvt_pk_f32_fp8_e32 v[144:145], v134
	v_cvt_pk_f32_fp8_e32 v[148:149], v135
	v_cvt_pk_f32_fp8_sdwa v[134:135], v135 src0_sel:WORD_1
	v_lshlrev_b32_e32 v150, 16, v138
	v_and_b32_e32 v151, 0xffff0000, v138
	v_lshlrev_b32_e32 v138, 16, v139
	v_and_b32_e32 v139, 0xffff0000, v139
	v_pk_fma_f32 v[138:139], v[146:147], s[0:1], v[138:139] op_sel_hi:[1,0,1]
	v_lshlrev_b32_e32 v146, 16, v140
	v_and_b32_e32 v147, 0xffff0000, v140
	v_lshlrev_b32_e32 v140, 16, v141
	v_and_b32_e32 v141, 0xffff0000, v141
	v_pk_fma_f32 v[134:135], v[134:135], s[0:1], v[140:141] op_sel_hi:[1,0,1]
	v_pk_fma_f32 v[8:9], v[138:139], s[86:87], v[8:9] op_sel_hi:[1,0,1]
	s_waitcnt vmcnt(0)
	v_mov_b64_e32 v[138:139], v[220:221]
	v_mov_b64_e32 v[140:141], v[222:223]
	v_pk_fma_f32 v[4:5], v[134:135], s[86:87], v[4:5] op_sel_hi:[1,0,1]
	v_cvt_pk_f32_fp8_e32 v[134:135], v136
	v_pk_fma_f32 v[146:147], v[148:149], s[0:1], v[146:147] op_sel_hi:[1,0,1]
	v_cvt_pk_f32_fp8_sdwa v[142:143], v136 src0_sel:WORD_1
	v_pk_fma_f32 v[144:145], v[144:145], s[0:1], v[150:151] op_sel_hi:[1,0,1]
	v_pk_fma_f32 v[2:3], v[146:147], s[86:87], v[2:3] op_sel_hi:[1,0,1]
	v_pk_fma_f32 v[6:7], v[144:145], s[86:87], v[6:7] op_sel_hi:[1,0,1]
	v_cvt_pk_f32_fp8_e32 v[144:145], v137
	v_cvt_pk_f32_fp8_sdwa v[136:137], v137 src0_sel:WORD_1
	s_waitcnt vmcnt(0)
	v_lshlrev_b32_e32 v146, 16, v138
	v_and_b32_e32 v147, 0xffff0000, v138
	v_pk_fma_f32 v[134:135], v[134:135], s[0:1], v[146:147] op_sel_hi:[1,0,1]
	v_lshlrev_b32_e32 v138, 16, v139
	v_and_b32_e32 v139, 0xffff0000, v139
	v_pk_fma_f32 v[18:19], v[134:135], s[86:87], v[18:19] op_sel_hi:[1,0,1]
	v_or_b32_e32 v134, 16, v132
	v_pk_fma_f32 v[138:139], v[142:143], s[0:1], v[138:139] op_sel_hi:[1,0,1]
	v_ashrrev_i32_e32 v135, 31, v134
	v_lshlrev_b32_e32 v142, 16, v140
	v_and_b32_e32 v143, 0xffff0000, v140
	v_lshlrev_b32_e32 v140, 16, v141
	v_and_b32_e32 v141, 0xffff0000, v141
	v_pk_fma_f32 v[20:21], v[138:139], s[86:87], v[20:21] op_sel_hi:[1,0,1]
	v_lshlrev_b64 v[138:139], 11, v[134:135]
	v_pk_fma_f32 v[142:143], v[144:145], s[0:1], v[142:143] op_sel_hi:[1,0,1]
	v_pk_fma_f32 v[136:137], v[136:137], s[0:1], v[140:141] op_sel_hi:[1,0,1]
	v_lshl_add_u64 v[134:135], s[28:29], 0, v[138:139]
	v_pk_fma_f32 v[16:17], v[136:137], s[86:87], v[16:17] op_sel_hi:[1,0,1]
	v_pk_fma_f32 v[14:15], v[142:143], s[86:87], v[14:15] op_sel_hi:[1,0,1]
	v_lshl_add_u64 v[134:135], v[134:135], 0, v[162:163]
	s_waitcnt vmcnt(0)
	v_mov_b64_e32 v[134:135], v[224:225]
	v_mov_b64_e32 v[136:137], v[226:227]
	v_lshl_add_u64 v[138:139], s[34:35], 0, v[138:139]
	v_lshl_add_u64 v[142:143], v[138:139], 0, v[164:165]
	s_waitcnt vmcnt(0)
	v_mov_b64_e32 v[138:139], v[228:229]
	v_mov_b64_e32 v[140:141], v[230:231]
	v_mov_b32_e32 v173, v8
	v_mov_b32_e32 v174, v6
	v_mov_b32_e32 v175, v9
	v_mov_b32_e32 v176, v2
	v_mov_b32_e32 v177, v5
	v_add_f32_e32 v197, v20, v21
	v_mov_b32_e32 v196, v15
	s_waitcnt vmcnt(1)
	v_cvt_pk_f32_fp8_sdwa v[146:147], v134 src0_sel:WORD_1
	v_cvt_pk_f32_fp8_e32 v[144:145], v134
	v_cvt_pk_f32_fp8_e32 v[148:149], v135
	v_cvt_pk_f32_fp8_sdwa v[134:135], v135 src0_sel:WORD_1
	s_waitcnt vmcnt(0)
	v_lshlrev_b32_e32 v150, 16, v138
	v_and_b32_e32 v151, 0xffff0000, v138
	v_lshlrev_b32_e32 v138, 16, v139
	v_and_b32_e32 v139, 0xffff0000, v139
	v_pk_fma_f32 v[138:139], v[146:147], s[0:1], v[138:139] op_sel_hi:[1,0,1]
	v_lshlrev_b32_e32 v146, 16, v140
	v_and_b32_e32 v147, 0xffff0000, v140
	v_lshlrev_b32_e32 v140, 16, v141
	v_and_b32_e32 v141, 0xffff0000, v141
	v_pk_fma_f32 v[134:135], v[134:135], s[0:1], v[140:141] op_sel_hi:[1,0,1]
	v_pk_fma_f32 v[40:41], v[138:139], s[86:87], v[40:41] op_sel_hi:[1,0,1]
	s_waitcnt vmcnt(0)
	v_mov_b64_e32 v[138:139], v[232:233]
	v_mov_b64_e32 v[140:141], v[234:235]
	v_pk_fma_f32 v[36:37], v[134:135], s[86:87], v[36:37] op_sel_hi:[1,0,1]
	v_cvt_pk_f32_fp8_e32 v[134:135], v136
	v_pk_fma_f32 v[146:147], v[148:149], s[0:1], v[146:147] op_sel_hi:[1,0,1]
	v_cvt_pk_f32_fp8_sdwa v[142:143], v136 src0_sel:WORD_1
	v_pk_fma_f32 v[144:145], v[144:145], s[0:1], v[150:151] op_sel_hi:[1,0,1]
	v_pk_fma_f32 v[34:35], v[146:147], s[86:87], v[34:35] op_sel_hi:[1,0,1]
	v_pk_fma_f32 v[38:39], v[144:145], s[86:87], v[38:39] op_sel_hi:[1,0,1]
	v_cvt_pk_f32_fp8_e32 v[144:145], v137
	v_cvt_pk_f32_fp8_sdwa v[136:137], v137 src0_sel:WORD_1
	s_waitcnt vmcnt(0)
	v_lshlrev_b32_e32 v146, 16, v138
	v_and_b32_e32 v147, 0xffff0000, v138
	v_pk_fma_f32 v[134:135], v[134:135], s[0:1], v[146:147] op_sel_hi:[1,0,1]
	v_lshlrev_b32_e32 v138, 16, v139
	v_and_b32_e32 v139, 0xffff0000, v139
	v_pk_fma_f32 v[46:47], v[134:135], s[86:87], v[46:47] op_sel_hi:[1,0,1]
	v_or_b32_e32 v134, 32, v132
	v_pk_fma_f32 v[138:139], v[142:143], s[0:1], v[138:139] op_sel_hi:[1,0,1]
	v_ashrrev_i32_e32 v135, 31, v134
	v_lshlrev_b32_e32 v142, 16, v140
	v_and_b32_e32 v143, 0xffff0000, v140
	v_lshlrev_b32_e32 v140, 16, v141
	v_and_b32_e32 v141, 0xffff0000, v141
	v_pk_fma_f32 v[48:49], v[138:139], s[86:87], v[48:49] op_sel_hi:[1,0,1]
	v_lshlrev_b64 v[138:139], 11, v[134:135]
	v_pk_fma_f32 v[142:143], v[144:145], s[0:1], v[142:143] op_sel_hi:[1,0,1]
	v_pk_fma_f32 v[136:137], v[136:137], s[0:1], v[140:141] op_sel_hi:[1,0,1]
	v_lshl_add_u64 v[134:135], s[28:29], 0, v[138:139]
	v_pk_fma_f32 v[44:45], v[136:137], s[86:87], v[44:45] op_sel_hi:[1,0,1]
	v_pk_fma_f32 v[42:43], v[142:143], s[86:87], v[42:43] op_sel_hi:[1,0,1]
	v_lshl_add_u64 v[134:135], v[134:135], 0, v[162:163]
	s_waitcnt vmcnt(0)
	v_mov_b64_e32 v[134:135], v[236:237]
	v_mov_b64_e32 v[136:137], v[238:239]
	v_lshl_add_u64 v[138:139], s[34:35], 0, v[138:139]
	v_lshl_add_u64 v[142:143], v[138:139], 0, v[164:165]
	s_waitcnt vmcnt(0)
	v_mov_b64_e32 v[138:139], v[240:241]
	v_mov_b64_e32 v[140:141], v[242:243]
	s_waitcnt vmcnt(1)
	v_cvt_pk_f32_fp8_sdwa v[146:147], v134 src0_sel:WORD_1
	v_cvt_pk_f32_fp8_e32 v[144:145], v134
	v_cvt_pk_f32_fp8_e32 v[148:149], v135
	v_cvt_pk_f32_fp8_sdwa v[134:135], v135 src0_sel:WORD_1
	s_waitcnt vmcnt(0)
	v_lshlrev_b32_e32 v150, 16, v138
	v_and_b32_e32 v151, 0xffff0000, v138
	v_lshlrev_b32_e32 v138, 16, v139
	v_and_b32_e32 v139, 0xffff0000, v139
	v_pk_fma_f32 v[138:139], v[146:147], s[0:1], v[138:139] op_sel_hi:[1,0,1]
	v_lshlrev_b32_e32 v146, 16, v140
	v_and_b32_e32 v147, 0xffff0000, v140
	v_lshlrev_b32_e32 v140, 16, v141
	v_and_b32_e32 v141, 0xffff0000, v141
	v_pk_fma_f32 v[134:135], v[134:135], s[0:1], v[140:141] op_sel_hi:[1,0,1]
	v_pk_fma_f32 v[64:65], v[138:139], s[86:87], v[64:65] op_sel_hi:[1,0,1]
	s_waitcnt vmcnt(0)
	v_mov_b64_e32 v[138:139], v[244:245]
	v_mov_b64_e32 v[140:141], v[246:247]
	s_mov_b32 s98, 0x18000
	s_mov_b32 s99, 0
	v_lshl_add_u64 v[212:213], v[248:249], 0, s[98:99]
	global_load_dwordx4 v[212:215], v[212:213], off
	s_mov_b32 s98, 0x18000
	s_mov_b32 s99, 0
	v_lshl_add_u64 v[216:217], v[250:251], 0, s[98:99]
	global_load_dwordx4 v[216:219], v[216:217], off
	s_mov_b32 s98, 0x18000
	s_mov_b32 s99, 0
	v_lshl_add_u64 v[220:221], v[250:251], 0, s[98:99]
	global_load_dwordx4 v[220:223], v[220:221], off offset:256
	s_mov_b32 s98, 0x40000
	s_mov_b32 s99, 0
	v_lshl_add_u64 v[224:225], v[248:249], 0, s[98:99]
	global_load_dwordx4 v[224:227], v[224:225], off
	s_mov_b32 s98, 0x40000
	s_mov_b32 s99, 0
	v_lshl_add_u64 v[228:229], v[250:251], 0, s[98:99]
	global_load_dwordx4 v[228:231], v[228:229], off
	s_mov_b32 s98, 0x40000
	s_mov_b32 s99, 0
	v_lshl_add_u64 v[232:233], v[250:251], 0, s[98:99]
	global_load_dwordx4 v[232:235], v[232:233], off offset:256
	s_mov_b32 s98, 0x48000
	s_mov_b32 s99, 0
	v_lshl_add_u64 v[236:237], v[248:249], 0, s[98:99]
	global_load_dwordx4 v[236:239], v[236:237], off
	s_mov_b32 s98, 0x48000
	s_mov_b32 s99, 0
	v_lshl_add_u64 v[240:241], v[250:251], 0, s[98:99]
	global_load_dwordx4 v[240:243], v[240:241], off
	s_mov_b32 s98, 0x48000
	s_mov_b32 s99, 0
	v_lshl_add_u64 v[244:245], v[250:251], 0, s[98:99]
	global_load_dwordx4 v[244:247], v[244:245], off offset:256
	v_pk_fma_f32 v[60:61], v[134:135], s[86:87], v[60:61] op_sel_hi:[1,0,1]
	v_cvt_pk_f32_fp8_e32 v[134:135], v136
	v_pk_fma_f32 v[146:147], v[148:149], s[0:1], v[146:147] op_sel_hi:[1,0,1]
	v_cvt_pk_f32_fp8_sdwa v[142:143], v136 src0_sel:WORD_1
	v_pk_fma_f32 v[144:145], v[144:145], s[0:1], v[150:151] op_sel_hi:[1,0,1]
	v_pk_fma_f32 v[58:59], v[146:147], s[86:87], v[58:59] op_sel_hi:[1,0,1]
	v_pk_fma_f32 v[62:63], v[144:145], s[86:87], v[62:63] op_sel_hi:[1,0,1]
	v_cvt_pk_f32_fp8_e32 v[144:145], v137
	v_cvt_pk_f32_fp8_sdwa v[136:137], v137 src0_sel:WORD_1
	s_waitcnt vmcnt(0)
	v_lshlrev_b32_e32 v146, 16, v138
	v_and_b32_e32 v147, 0xffff0000, v138
	v_pk_fma_f32 v[134:135], v[134:135], s[0:1], v[146:147] op_sel_hi:[1,0,1]
	v_lshlrev_b32_e32 v138, 16, v139
	v_and_b32_e32 v139, 0xffff0000, v139
	v_pk_fma_f32 v[70:71], v[134:135], s[86:87], v[70:71] op_sel_hi:[1,0,1]
	v_or_b32_e32 v134, 48, v132
	v_pk_fma_f32 v[138:139], v[142:143], s[0:1], v[138:139] op_sel_hi:[1,0,1]
	v_ashrrev_i32_e32 v135, 31, v134
	v_lshlrev_b32_e32 v142, 16, v140
	v_and_b32_e32 v143, 0xffff0000, v140
	v_lshlrev_b32_e32 v140, 16, v141
	v_and_b32_e32 v141, 0xffff0000, v141
	v_pk_fma_f32 v[72:73], v[138:139], s[86:87], v[72:73] op_sel_hi:[1,0,1]
	v_lshlrev_b64 v[138:139], 11, v[134:135]
	v_pk_fma_f32 v[142:143], v[144:145], s[0:1], v[142:143] op_sel_hi:[1,0,1]
	v_pk_fma_f32 v[136:137], v[136:137], s[0:1], v[140:141] op_sel_hi:[1,0,1]
	v_lshl_add_u64 v[134:135], s[28:29], 0, v[138:139]
	v_pk_fma_f32 v[68:69], v[136:137], s[86:87], v[68:69] op_sel_hi:[1,0,1]
	v_pk_fma_f32 v[66:67], v[142:143], s[86:87], v[66:67] op_sel_hi:[1,0,1]
	v_lshl_add_u64 v[134:135], v[134:135], 0, v[162:163]
	s_waitcnt vmcnt(0)
	v_mov_b64_e32 v[134:135], v[212:213]
	v_mov_b64_e32 v[136:137], v[214:215]
	v_lshl_add_u64 v[138:139], s[34:35], 0, v[138:139]
	v_lshl_add_u64 v[142:143], v[138:139], 0, v[164:165]
	s_waitcnt vmcnt(0)
	v_mov_b64_e32 v[138:139], v[216:217]
	v_mov_b64_e32 v[140:141], v[218:219]
	s_waitcnt vmcnt(1)
	v_cvt_pk_f32_fp8_sdwa v[146:147], v134 src0_sel:WORD_1
	v_cvt_pk_f32_fp8_e32 v[144:145], v134
	v_cvt_pk_f32_fp8_e32 v[148:149], v135
	v_cvt_pk_f32_fp8_sdwa v[134:135], v135 src0_sel:WORD_1
	s_waitcnt vmcnt(0)
	v_lshlrev_b32_e32 v150, 16, v138
	v_and_b32_e32 v151, 0xffff0000, v138
	v_lshlrev_b32_e32 v138, 16, v139
	v_and_b32_e32 v139, 0xffff0000, v139
	v_pk_fma_f32 v[138:139], v[146:147], s[0:1], v[138:139] op_sel_hi:[1,0,1]
	v_lshlrev_b32_e32 v146, 16, v140
	v_and_b32_e32 v147, 0xffff0000, v140
	v_lshlrev_b32_e32 v140, 16, v141
	v_and_b32_e32 v141, 0xffff0000, v141
	v_pk_fma_f32 v[134:135], v[134:135], s[0:1], v[140:141] op_sel_hi:[1,0,1]
	v_pk_fma_f32 v[88:89], v[138:139], s[86:87], v[88:89] op_sel_hi:[1,0,1]
	s_waitcnt vmcnt(0)
	v_mov_b64_e32 v[138:139], v[220:221]
	v_mov_b64_e32 v[140:141], v[222:223]
	v_pk_fma_f32 v[84:85], v[134:135], s[86:87], v[84:85] op_sel_hi:[1,0,1]
	v_cvt_pk_f32_fp8_e32 v[134:135], v136
	v_pk_fma_f32 v[146:147], v[148:149], s[0:1], v[146:147] op_sel_hi:[1,0,1]
	v_cvt_pk_f32_fp8_sdwa v[142:143], v136 src0_sel:WORD_1
	v_pk_fma_f32 v[144:145], v[144:145], s[0:1], v[150:151] op_sel_hi:[1,0,1]
	v_pk_fma_f32 v[82:83], v[146:147], s[86:87], v[82:83] op_sel_hi:[1,0,1]
	v_pk_fma_f32 v[86:87], v[144:145], s[86:87], v[86:87] op_sel_hi:[1,0,1]
	v_cvt_pk_f32_fp8_e32 v[144:145], v137
	v_cvt_pk_f32_fp8_sdwa v[136:137], v137 src0_sel:WORD_1
	s_waitcnt vmcnt(0)
	v_lshlrev_b32_e32 v146, 16, v138
	v_and_b32_e32 v147, 0xffff0000, v138
	v_pk_fma_f32 v[134:135], v[134:135], s[0:1], v[146:147] op_sel_hi:[1,0,1]
	v_lshlrev_b32_e32 v138, 16, v139
	v_and_b32_e32 v139, 0xffff0000, v139
	v_pk_fma_f32 v[94:95], v[134:135], s[86:87], v[94:95] op_sel_hi:[1,0,1]
	v_add_u32_e32 v134, 0x80, v132
	v_pk_fma_f32 v[138:139], v[142:143], s[0:1], v[138:139] op_sel_hi:[1,0,1]
	v_ashrrev_i32_e32 v135, 31, v134
	v_lshlrev_b32_e32 v142, 16, v140
	v_and_b32_e32 v143, 0xffff0000, v140
	v_lshlrev_b32_e32 v140, 16, v141
	v_and_b32_e32 v141, 0xffff0000, v141
	v_pk_fma_f32 v[96:97], v[138:139], s[86:87], v[96:97] op_sel_hi:[1,0,1]
	v_lshlrev_b64 v[138:139], 11, v[134:135]
	v_pk_fma_f32 v[142:143], v[144:145], s[0:1], v[142:143] op_sel_hi:[1,0,1]
	v_pk_fma_f32 v[136:137], v[136:137], s[0:1], v[140:141] op_sel_hi:[1,0,1]
	v_lshl_add_u64 v[134:135], s[28:29], 0, v[138:139]
	v_pk_fma_f32 v[92:93], v[136:137], s[86:87], v[92:93] op_sel_hi:[1,0,1]
	v_pk_fma_f32 v[90:91], v[142:143], s[86:87], v[90:91] op_sel_hi:[1,0,1]
	v_lshl_add_u64 v[134:135], v[134:135], 0, v[162:163]
	s_waitcnt vmcnt(0)
	v_mov_b64_e32 v[134:135], v[224:225]
	v_mov_b64_e32 v[136:137], v[226:227]
	v_lshl_add_u64 v[138:139], s[34:35], 0, v[138:139]
	v_lshl_add_u64 v[142:143], v[138:139], 0, v[164:165]
	s_waitcnt vmcnt(0)
	v_mov_b64_e32 v[138:139], v[228:229]
	v_mov_b64_e32 v[140:141], v[230:231]
	s_waitcnt vmcnt(1)
	v_cvt_pk_f32_fp8_sdwa v[146:147], v134 src0_sel:WORD_1
	v_cvt_pk_f32_fp8_e32 v[144:145], v134
	v_cvt_pk_f32_fp8_e32 v[148:149], v135
	v_cvt_pk_f32_fp8_sdwa v[134:135], v135 src0_sel:WORD_1
	s_waitcnt vmcnt(0)
	v_lshlrev_b32_e32 v150, 16, v138
	v_and_b32_e32 v151, 0xffff0000, v138
	v_lshlrev_b32_e32 v138, 16, v139
	v_and_b32_e32 v139, 0xffff0000, v139
	v_pk_fma_f32 v[138:139], v[146:147], s[0:1], v[138:139] op_sel_hi:[1,0,1]
	v_lshlrev_b32_e32 v146, 16, v140
	v_and_b32_e32 v147, 0xffff0000, v140
	v_lshlrev_b32_e32 v140, 16, v141
	v_and_b32_e32 v141, 0xffff0000, v141
	v_pk_fma_f32 v[134:135], v[134:135], s[0:1], v[140:141] op_sel_hi:[1,0,1]
	v_pk_fma_f32 v[112:113], v[138:139], s[86:87], v[112:113] op_sel_hi:[1,0,1]
	s_waitcnt vmcnt(0)
	v_mov_b64_e32 v[138:139], v[232:233]
	v_mov_b64_e32 v[140:141], v[234:235]
	v_pk_fma_f32 v[108:109], v[134:135], s[86:87], v[108:109] op_sel_hi:[1,0,1]
	v_cvt_pk_f32_fp8_e32 v[134:135], v136
	v_pk_fma_f32 v[146:147], v[148:149], s[0:1], v[146:147] op_sel_hi:[1,0,1]
	v_cvt_pk_f32_fp8_sdwa v[142:143], v136 src0_sel:WORD_1
	v_pk_fma_f32 v[144:145], v[144:145], s[0:1], v[150:151] op_sel_hi:[1,0,1]
	v_pk_fma_f32 v[106:107], v[146:147], s[86:87], v[106:107] op_sel_hi:[1,0,1]
	v_pk_fma_f32 v[110:111], v[144:145], s[86:87], v[110:111] op_sel_hi:[1,0,1]
	v_cvt_pk_f32_fp8_e32 v[144:145], v137
	v_cvt_pk_f32_fp8_sdwa v[136:137], v137 src0_sel:WORD_1
	s_waitcnt vmcnt(0)
	v_lshlrev_b32_e32 v146, 16, v138
	v_and_b32_e32 v147, 0xffff0000, v138
	v_pk_fma_f32 v[134:135], v[134:135], s[0:1], v[146:147] op_sel_hi:[1,0,1]
	v_lshlrev_b32_e32 v138, 16, v139
	v_and_b32_e32 v139, 0xffff0000, v139
	v_pk_fma_f32 v[122:123], v[134:135], s[86:87], v[122:123] op_sel_hi:[1,0,1]
	v_add_u32_e32 v134, 0x90, v132
	v_pk_fma_f32 v[138:139], v[142:143], s[0:1], v[138:139] op_sel_hi:[1,0,1]
	v_ashrrev_i32_e32 v135, 31, v134
	v_lshlrev_b32_e32 v142, 16, v140
	v_and_b32_e32 v143, 0xffff0000, v140
	v_lshlrev_b32_e32 v140, 16, v141
	v_and_b32_e32 v141, 0xffff0000, v141
	v_pk_fma_f32 v[124:125], v[138:139], s[86:87], v[124:125] op_sel_hi:[1,0,1]
	v_lshlrev_b64 v[138:139], 11, v[134:135]
	v_pk_fma_f32 v[142:143], v[144:145], s[0:1], v[142:143] op_sel_hi:[1,0,1]
	v_pk_fma_f32 v[136:137], v[136:137], s[0:1], v[140:141] op_sel_hi:[1,0,1]
	v_lshl_add_u64 v[134:135], s[28:29], 0, v[138:139]
	v_pk_fma_f32 v[116:117], v[136:137], s[86:87], v[116:117] op_sel_hi:[1,0,1]
	v_pk_fma_f32 v[114:115], v[142:143], s[86:87], v[114:115] op_sel_hi:[1,0,1]
	v_lshl_add_u64 v[134:135], v[134:135], 0, v[162:163]
	s_waitcnt vmcnt(0)
	v_mov_b64_e32 v[134:135], v[236:237]
	v_mov_b64_e32 v[136:137], v[238:239]
	v_lshl_add_u64 v[138:139], s[34:35], 0, v[138:139]
	v_lshl_add_u64 v[142:143], v[138:139], 0, v[164:165]
	s_waitcnt vmcnt(0)
	v_mov_b64_e32 v[138:139], v[240:241]
	v_mov_b64_e32 v[140:141], v[242:243]
	s_waitcnt vmcnt(1)
	v_cvt_pk_f32_fp8_sdwa v[146:147], v134 src0_sel:WORD_1
	v_cvt_pk_f32_fp8_e32 v[144:145], v134
	v_cvt_pk_f32_fp8_e32 v[148:149], v135
	v_cvt_pk_f32_fp8_sdwa v[134:135], v135 src0_sel:WORD_1
	s_waitcnt vmcnt(0)
	v_lshlrev_b32_e32 v150, 16, v138
	v_and_b32_e32 v151, 0xffff0000, v138
	v_lshlrev_b32_e32 v138, 16, v139
	v_and_b32_e32 v139, 0xffff0000, v139
	v_pk_fma_f32 v[138:139], v[146:147], s[0:1], v[138:139] op_sel_hi:[1,0,1]
	v_lshlrev_b32_e32 v146, 16, v140
	v_and_b32_e32 v147, 0xffff0000, v140
	v_lshlrev_b32_e32 v140, 16, v141
	v_and_b32_e32 v141, 0xffff0000, v141
	v_pk_fma_f32 v[134:135], v[134:135], s[0:1], v[140:141] op_sel_hi:[1,0,1]
	v_pk_fma_f32 v[128:129], v[138:139], s[86:87], v[128:129] op_sel_hi:[1,0,1]
	s_waitcnt vmcnt(0)
	v_mov_b64_e32 v[138:139], v[244:245]
	v_mov_b64_e32 v[140:141], v[246:247]
	s_mov_b32 s98, 0x50000
	s_mov_b32 s99, 0
	v_lshl_add_u64 v[212:213], v[248:249], 0, s[98:99]
	global_load_dwordx4 v[212:215], v[212:213], off
	s_mov_b32 s98, 0x50000
	s_mov_b32 s99, 0
	v_lshl_add_u64 v[216:217], v[250:251], 0, s[98:99]
	global_load_dwordx4 v[216:219], v[216:217], off
	s_mov_b32 s98, 0x50000
	s_mov_b32 s99, 0
	v_lshl_add_u64 v[220:221], v[250:251], 0, s[98:99]
	global_load_dwordx4 v[220:223], v[220:221], off offset:256
	s_mov_b32 s98, 0x58000
	s_mov_b32 s99, 0
	v_lshl_add_u64 v[224:225], v[248:249], 0, s[98:99]
	global_load_dwordx4 v[224:227], v[224:225], off
	s_mov_b32 s98, 0x58000
	s_mov_b32 s99, 0
	v_lshl_add_u64 v[228:229], v[250:251], 0, s[98:99]
	global_load_dwordx4 v[228:231], v[228:229], off
	s_mov_b32 s98, 0x58000
	s_mov_b32 s99, 0
	v_lshl_add_u64 v[232:233], v[250:251], 0, s[98:99]
	global_load_dwordx4 v[232:235], v[232:233], off offset:256
	v_pk_fma_f32 v[120:121], v[134:135], s[86:87], v[120:121] op_sel_hi:[1,0,1]
	v_cvt_pk_f32_fp8_e32 v[134:135], v136
	v_pk_fma_f32 v[146:147], v[148:149], s[0:1], v[146:147] op_sel_hi:[1,0,1]
	v_cvt_pk_f32_fp8_sdwa v[142:143], v136 src0_sel:WORD_1
	v_pk_fma_f32 v[144:145], v[144:145], s[0:1], v[150:151] op_sel_hi:[1,0,1]
	v_pk_fma_f32 v[118:119], v[146:147], s[86:87], v[118:119] op_sel_hi:[1,0,1]
	v_pk_fma_f32 v[126:127], v[144:145], s[86:87], v[126:127] op_sel_hi:[1,0,1]
	v_cvt_pk_f32_fp8_e32 v[144:145], v137
	v_cvt_pk_f32_fp8_sdwa v[136:137], v137 src0_sel:WORD_1
	s_waitcnt vmcnt(0)
	v_lshlrev_b32_e32 v146, 16, v138
	v_and_b32_e32 v147, 0xffff0000, v138
	v_pk_fma_f32 v[134:135], v[134:135], s[0:1], v[146:147] op_sel_hi:[1,0,1]
	v_lshlrev_b32_e32 v138, 16, v139
	v_and_b32_e32 v139, 0xffff0000, v139
	v_pk_fma_f32 v[102:103], v[134:135], s[86:87], v[102:103] op_sel_hi:[1,0,1]
	v_add_u32_e32 v134, 0xa0, v132
	v_pk_fma_f32 v[138:139], v[142:143], s[0:1], v[138:139] op_sel_hi:[1,0,1]
	v_ashrrev_i32_e32 v135, 31, v134
	v_lshlrev_b32_e32 v142, 16, v140
	v_and_b32_e32 v143, 0xffff0000, v140
	v_lshlrev_b32_e32 v140, 16, v141
	v_and_b32_e32 v141, 0xffff0000, v141
	v_pk_fma_f32 v[104:105], v[138:139], s[86:87], v[104:105] op_sel_hi:[1,0,1]
	v_lshlrev_b64 v[138:139], 11, v[134:135]
	v_pk_fma_f32 v[142:143], v[144:145], s[0:1], v[142:143] op_sel_hi:[1,0,1]
	v_pk_fma_f32 v[136:137], v[136:137], s[0:1], v[140:141] op_sel_hi:[1,0,1]
	v_lshl_add_u64 v[134:135], s[28:29], 0, v[138:139]
	v_pk_fma_f32 v[100:101], v[136:137], s[86:87], v[100:101] op_sel_hi:[1,0,1]
	v_pk_fma_f32 v[98:99], v[142:143], s[86:87], v[98:99] op_sel_hi:[1,0,1]
	v_lshl_add_u64 v[134:135], v[134:135], 0, v[162:163]
	s_waitcnt vmcnt(0)
	v_mov_b64_e32 v[134:135], v[212:213]
	v_mov_b64_e32 v[136:137], v[214:215]
	v_lshl_add_u64 v[138:139], s[34:35], 0, v[138:139]
	v_lshl_add_u64 v[142:143], v[138:139], 0, v[164:165]
	s_waitcnt vmcnt(0)
	v_mov_b64_e32 v[138:139], v[216:217]
	v_mov_b64_e32 v[140:141], v[218:219]
	v_add_u32_e32 v132, 0xb0, v132
	v_ashrrev_i32_e32 v133, 31, v132
	s_waitcnt vmcnt(1)
	v_cvt_pk_f32_fp8_sdwa v[146:147], v134 src0_sel:WORD_1
	v_cvt_pk_f32_fp8_e32 v[144:145], v134
	v_cvt_pk_f32_fp8_e32 v[148:149], v135
	v_cvt_pk_f32_fp8_sdwa v[134:135], v135 src0_sel:WORD_1
	s_waitcnt vmcnt(0)
	v_lshlrev_b32_e32 v150, 16, v138
	v_and_b32_e32 v151, 0xffff0000, v138
	v_lshlrev_b32_e32 v138, 16, v139
	v_and_b32_e32 v139, 0xffff0000, v139
	v_pk_fma_f32 v[138:139], v[146:147], s[0:1], v[138:139] op_sel_hi:[1,0,1]
	v_lshlrev_b32_e32 v146, 16, v140
	v_and_b32_e32 v147, 0xffff0000, v140
	v_lshlrev_b32_e32 v140, 16, v141
	v_and_b32_e32 v141, 0xffff0000, v141
	v_pk_fma_f32 v[134:135], v[134:135], s[0:1], v[140:141] op_sel_hi:[1,0,1]
	v_pk_fma_f32 v[80:81], v[138:139], s[86:87], v[80:81] op_sel_hi:[1,0,1]
	s_waitcnt vmcnt(0)
	v_mov_b64_e32 v[138:139], v[220:221]
	v_mov_b64_e32 v[140:141], v[222:223]
	v_pk_fma_f32 v[144:145], v[144:145], s[0:1], v[150:151] op_sel_hi:[1,0,1]
	v_cvt_pk_f32_fp8_sdwa v[142:143], v136 src0_sel:WORD_1
	v_pk_fma_f32 v[78:79], v[144:145], s[86:87], v[78:79] op_sel_hi:[1,0,1]
	v_pk_fma_f32 v[76:77], v[134:135], s[86:87], v[76:77] op_sel_hi:[1,0,1]
	v_cvt_pk_f32_fp8_e32 v[134:135], v136
	v_cvt_pk_f32_fp8_e32 v[144:145], v137
	v_cvt_pk_f32_fp8_sdwa v[136:137], v137 src0_sel:WORD_1
	v_pk_fma_f32 v[146:147], v[148:149], s[0:1], v[146:147] op_sel_hi:[1,0,1]
	s_nop 0
	v_pk_fma_f32 v[74:75], v[146:147], s[86:87], v[74:75] op_sel_hi:[1,0,1]
	s_waitcnt vmcnt(0)
	v_lshlrev_b32_e32 v146, 16, v138
	v_and_b32_e32 v147, 0xffff0000, v138
	v_lshlrev_b32_e32 v138, 16, v139
	v_and_b32_e32 v139, 0xffff0000, v139
	v_pk_fma_f32 v[138:139], v[142:143], s[0:1], v[138:139] op_sel_hi:[1,0,1]
	v_lshlrev_b32_e32 v142, 16, v140
	v_and_b32_e32 v143, 0xffff0000, v140
	v_lshlrev_b32_e32 v140, 16, v141
	v_and_b32_e32 v141, 0xffff0000, v141
	v_pk_fma_f32 v[136:137], v[136:137], s[0:1], v[140:141] op_sel_hi:[1,0,1]
	v_pk_fma_f32 v[134:135], v[134:135], s[0:1], v[146:147] op_sel_hi:[1,0,1]
	v_pk_fma_f32 v[52:53], v[136:137], s[86:87], v[52:53] op_sel_hi:[1,0,1]
	v_lshlrev_b64 v[136:137], 11, v[132:133]
	v_pk_fma_f32 v[142:143], v[144:145], s[0:1], v[142:143] op_sel_hi:[1,0,1]
	v_lshl_add_u64 v[132:133], s[28:29], 0, v[136:137]
	v_pk_fma_f32 v[56:57], v[138:139], s[86:87], v[56:57] op_sel_hi:[1,0,1]
	v_pk_fma_f32 v[54:55], v[134:135], s[86:87], v[54:55] op_sel_hi:[1,0,1]
	v_pk_fma_f32 v[50:51], v[142:143], s[86:87], v[50:51] op_sel_hi:[1,0,1]
	v_lshl_add_u64 v[132:133], v[132:133], 0, v[162:163]
	s_waitcnt vmcnt(0)
	v_mov_b64_e32 v[132:133], v[224:225]
	v_mov_b64_e32 v[134:135], v[226:227]
	v_lshl_add_u64 v[136:137], s[34:35], 0, v[136:137]
	v_lshl_add_u64 v[140:141], v[136:137], 0, v[164:165]
	s_waitcnt vmcnt(0)
	v_mov_b64_e32 v[136:137], v[228:229]
	v_mov_b64_e32 v[138:139], v[230:231]
	s_waitcnt vmcnt(1)
	v_cvt_pk_f32_fp8_sdwa v[144:145], v132 src0_sel:WORD_1
	v_cvt_pk_f32_fp8_e32 v[142:143], v132
	v_cvt_pk_f32_fp8_e32 v[146:147], v133
	v_cvt_pk_f32_fp8_sdwa v[132:133], v133 src0_sel:WORD_1
	s_waitcnt vmcnt(0)
	v_lshlrev_b32_e32 v148, 16, v136
	v_and_b32_e32 v149, 0xffff0000, v136
	v_lshlrev_b32_e32 v136, 16, v137
	v_and_b32_e32 v137, 0xffff0000, v137
	v_pk_fma_f32 v[136:137], v[144:145], s[0:1], v[136:137] op_sel_hi:[1,0,1]
	v_lshlrev_b32_e32 v144, 16, v138
	v_and_b32_e32 v145, 0xffff0000, v138
	v_lshlrev_b32_e32 v138, 16, v139
	v_and_b32_e32 v139, 0xffff0000, v139
	v_pk_fma_f32 v[132:133], v[132:133], s[0:1], v[138:139] op_sel_hi:[1,0,1]
	v_pk_fma_f32 v[32:33], v[136:137], s[86:87], v[32:33] op_sel_hi:[1,0,1]
	s_waitcnt vmcnt(0)
	v_mov_b64_e32 v[136:137], v[232:233]
	v_mov_b64_e32 v[138:139], v[234:235]
	v_pk_fma_f32 v[142:143], v[142:143], s[0:1], v[148:149] op_sel_hi:[1,0,1]
	v_cvt_pk_f32_fp8_sdwa v[140:141], v134 src0_sel:WORD_1
	v_pk_fma_f32 v[30:31], v[142:143], s[86:87], v[30:31] op_sel_hi:[1,0,1]
	v_pk_fma_f32 v[28:29], v[132:133], s[86:87], v[28:29] op_sel_hi:[1,0,1]
	v_cvt_pk_f32_fp8_e32 v[132:133], v134
	v_cvt_pk_f32_fp8_e32 v[142:143], v135
	v_cvt_pk_f32_fp8_sdwa v[134:135], v135 src0_sel:WORD_1
	v_pk_fma_f32 v[144:145], v[146:147], s[0:1], v[144:145] op_sel_hi:[1,0,1]
	s_nop 0
	v_pk_fma_f32 v[26:27], v[144:145], s[86:87], v[26:27] op_sel_hi:[1,0,1]
	s_waitcnt vmcnt(0)
	v_lshlrev_b32_e32 v144, 16, v136
	v_and_b32_e32 v145, 0xffff0000, v136
	v_lshlrev_b32_e32 v136, 16, v137
	v_and_b32_e32 v137, 0xffff0000, v137
	v_pk_fma_f32 v[136:137], v[140:141], s[0:1], v[136:137] op_sel_hi:[1,0,1]
	v_lshlrev_b32_e32 v140, 16, v138
	v_and_b32_e32 v141, 0xffff0000, v138
	v_lshlrev_b32_e32 v138, 16, v139
	v_and_b32_e32 v139, 0xffff0000, v139
	v_pk_fma_f32 v[132:133], v[132:133], s[0:1], v[144:145] op_sel_hi:[1,0,1]
	v_pk_fma_f32 v[140:141], v[142:143], s[0:1], v[140:141] op_sel_hi:[1,0,1]
	v_pk_fma_f32 v[134:135], v[134:135], s[0:1], v[138:139] op_sel_hi:[1,0,1]
	v_readlane_b32 s0, v255, 18
	v_readlane_b32 s1, v255, 19
	v_pk_fma_f32 v[22:23], v[132:133], s[86:87], v[22:23] op_sel_hi:[1,0,1]
	v_pk_fma_f32 v[12:13], v[134:135], s[86:87], v[12:13] op_sel_hi:[1,0,1]
	v_lshl_add_u64 v[132:133], s[0:1], 0, v[130:131]
	s_mov_b64 s[0:1], 0x2000
	v_lshl_add_u64 v[130:131], s[4:5], 0, v[130:131]
	v_lshl_add_u64 v[134:135], v[132:133], 0, s[0:1]
	v_lshl_add_u64 v[142:143], v[130:131], 0, s[0:1]
	s_movk_i32 s0, 0x2000
	v_add_co_u32_e32 v132, vcc, s0, v132
	v_pk_fma_f32 v[24:25], v[136:137], s[86:87], v[24:25] op_sel_hi:[1,0,1]
	s_nop 0
	v_addc_co_u32_e32 v133, vcc, 0, v133, vcc
	v_add_co_u32_e32 v130, vcc, s0, v130
	v_pk_fma_f32 v[10:11], v[140:141], s[86:87], v[10:11] op_sel_hi:[1,0,1]
	s_nop 0
	v_addc_co_u32_e32 v131, vcc, 0, v131, vcc
	global_load_dwordx4 v[154:157], v[132:133], off
	global_load_dwordx4 v[146:149], v[134:135], off offset:16
	global_load_dwordx4 v[158:161], v[130:131], off
	global_load_dwordx4 v[150:153], v[142:143], off offset:16
	s_nop 0
	global_load_dwordx4 v[130:133], v[134:135], off offset:528
	global_load_dwordx4 v[138:141], v[134:135], off offset:512
	s_nop 0
	global_load_dwordx4 v[134:137], v[142:143], off offset:528
	s_nop 0
	global_load_dwordx4 v[142:145], v[142:143], off offset:512
	v_cmp_lt_i32_e32 vcc, v170, v171
	s_lshl_b32 s0, s38, 3
	s_add_i32 s4, s0, 0
	v_cndmask_b32_e32 v170, v205, v170, vcc
	v_cmp_lt_i32_e32 vcc, v172, v171
	v_lshlrev_b32_e32 v170, 2, v170
	s_nop 0
	v_cndmask_b32_e32 v171, v205, v172, vcc
	v_mov_b32_e32 v172, v7
	v_pk_add_f32 v[172:173], v[172:173], v[174:175]
	v_mov_b32_e32 v174, v3
	v_mov_b32_e32 v175, v4
	v_pk_add_f32 v[174:175], v[174:175], v[176:177]
	v_add_f32_e32 v172, v172, v173
	v_pk_add_f32 v[174:175], v[174:175], v[174:175] op_sel_hi:[0,1]
	v_add_f32_e32 v173, 0, v172
	v_add_f32_e32 v177, v18, v19
	v_mov_b32_e32 v176, v14
	v_mov_b32_e32 v174, v16
	v_mov_b32_e32 v172, v17
	v_pk_add_f32 v[176:177], v[176:177], v[196:197]
	v_pk_add_f32 v[172:173], v[174:175], v[172:173]
	v_lshlrev_b32_e32 v171, 2, v171
	v_pk_add_f32 v[172:173], v[176:177], v[172:173]
	v_cmp_gt_u32_e32 vcc, 16, v169
	v_add_f32_e32 v172, v172, v173
	ds_bpermute_b32 v173, v170, v172
	s_waitcnt lgkmcnt(0)
	v_add_f32_e32 v172, v172, v173
	ds_bpermute_b32 v173, v171, v172
	s_waitcnt lgkmcnt(0)
	v_add_f32_e32 v172, v172, v173
	v_fmamk_f32 v174, v172, 0xbc800000, v9
	v_fmamk_f32 v176, v172, 0xbc800000, v7
	v_fmamk_f32 v173, v172, 0xbc800000, v8
	v_fmamk_f32 v175, v172, 0xbc800000, v6
	v_mul_f32_e32 v176, v176, v176
	v_mul_f32_e32 v174, v174, v174
	v_fmac_f32_e32 v176, v175, v175
	v_fmac_f32_e32 v174, v173, v173
	v_fmamk_f32 v175, v172, 0xbc800000, v5
	v_fmamk_f32 v177, v172, 0xbc800000, v3
	v_add_f32_e32 v173, v176, v174
	v_fmamk_f32 v174, v172, 0xbc800000, v4
	v_fmamk_f32 v176, v172, 0xbc800000, v2
	v_mul_f32_e32 v177, v177, v177
	v_mul_f32_e32 v175, v175, v175
	v_fmac_f32_e32 v177, v176, v176
	v_fmac_f32_e32 v175, v174, v174
	v_add_f32_e32 v174, v177, v175
	v_fmamk_f32 v175, v172, 0xbc800000, v21
	v_fmamk_f32 v177, v172, 0xbc800000, v19
	v_add_f32_e32 v173, v173, v174
	v_fmamk_f32 v174, v172, 0xbc800000, v20
	v_fmamk_f32 v176, v172, 0xbc800000, v18
	v_mul_f32_e32 v177, v177, v177
	v_mul_f32_e32 v175, v175, v175
	v_fmac_f32_e32 v177, v176, v176
	v_fmac_f32_e32 v175, v174, v174
	v_add_f32_e32 v174, v177, v175
	v_fmamk_f32 v175, v172, 0xbc800000, v17
	v_fmamk_f32 v177, v172, 0xbc800000, v15
	v_add_f32_e32 v173, v174, v173
	v_fmamk_f32 v174, v172, 0xbc800000, v16
	v_fmamk_f32 v176, v172, 0xbc800000, v14
	v_mul_f32_e32 v177, v177, v177
	v_mul_f32_e32 v175, v175, v175
	v_fmac_f32_e32 v177, v176, v176
	v_fmac_f32_e32 v175, v174, v174
	v_add_f32_e32 v174, v177, v175
	v_add_f32_e32 v173, v174, v173
	ds_bpermute_b32 v174, v170, v173
	s_waitcnt lgkmcnt(0)
	v_add_f32_e32 v173, v173, v174
	ds_bpermute_b32 v174, v171, v173
	s_and_saveexec_b64 s[0:1], vcc
	s_mov_b64 s[38:39], s[62:63]
	s_cbranch_execz .LBB0_1233
	s_lshl_b32 s5, s82, 11
	s_add_i32 s5, s4, s5
	v_mul_f32_e32 v172, 0x3c800000, v172
	v_lshl_add_u32 v175, v167, 5, s5
	s_waitcnt lgkmcnt(0)
	v_add_f32_e32 v173, v173, v174
	ds_write_b64 v175, v[172:173]

.LBB0_1296:
	s_add_u32 s0, s74, s34
	s_addc_u32 s1, s75, s35
	s_add_u32 s8, s0, 0x12c00000
	s_addc_u32 s9, s1, 0
	s_add_u32 s0, s74, s28
	s_addc_u32 s1, s75, s29
	v_lshrrev_b32_e32 v130, 1, v164
	s_add_u32 s6, s0, 0x9c00000
	v_and_b32_e32 v130, 24, v130
	s_addc_u32 s7, s1, 0
	s_lshl_b32 s0, s12, 8
	v_lshl_or_b32 v130, s38, 5, v130
	v_lshl_or_b32 v131, s38, 6, v144
	s_lshl_b32 s20, s95, 8
	v_or_b32_e32 v130, s0, v130
	v_or_b32_e32 v134, s0, v131
	s_add_i32 s0, s20, s84
	v_or_b32_e32 v136, s0, v165
	v_ashrrev_i32_e32 v137, 31, v136
	v_lshlrev_b64 v[132:133], 11, v[136:137]
	v_ashrrev_i32_e32 v135, 31, v134
	v_lshl_add_u64 v[138:139], s[8:9], 0, v[132:133]
	v_lshl_add_u64 v[138:139], v[138:139], 0, v[134:135]
	s_barrier
	v_ashrrev_i32_e32 v131, 31, v130
	v_mov_b64_e32 v[248:249], v[138:139]
	v_lshl_add_u64 v[142:143], s[6:7], 0, v[132:133]
	v_lshlrev_b64 v[132:133], 1, v[130:131]
	v_lshl_add_u64 v[146:147], v[142:143], 0, v[132:133]
	v_mov_b64_e32 v[250:251], v[146:147]
	v_mov_b64_e32 v[212:213], v[248:249]
	global_load_dwordx4 v[212:215], v[212:213], off
	v_mov_b64_e32 v[216:217], v[250:251]
	global_load_dwordx4 v[216:219], v[216:217], off
	v_mov_b64_e32 v[220:221], v[250:251]
	global_load_dwordx4 v[220:223], v[220:221], off offset:256
	s_mov_b32 s98, 0x8000
	s_mov_b32 s99, 0
	v_lshl_add_u64 v[224:225], v[248:249], 0, s[98:99]
	global_load_dwordx4 v[224:227], v[224:225], off
	s_mov_b32 s98, 0x8000
	s_mov_b32 s99, 0
	v_lshl_add_u64 v[228:229], v[250:251], 0, s[98:99]
	global_load_dwordx4 v[228:231], v[228:229], off
	s_mov_b32 s98, 0x8000
	s_mov_b32 s99, 0
	v_lshl_add_u64 v[232:233], v[250:251], 0, s[98:99]
	global_load_dwordx4 v[232:235], v[232:233], off offset:256
	s_mov_b32 s98, 0x10000
	s_mov_b32 s99, 0
	v_lshl_add_u64 v[236:237], v[248:249], 0, s[98:99]
	global_load_dwordx4 v[236:239], v[236:237], off
	s_mov_b32 s98, 0x10000
	s_mov_b32 s99, 0
	v_lshl_add_u64 v[240:241], v[250:251], 0, s[98:99]
	global_load_dwordx4 v[240:243], v[240:241], off
	s_mov_b32 s98, 0x10000
	s_mov_b32 s99, 0
	v_lshl_add_u64 v[244:245], v[250:251], 0, s[98:99]
	global_load_dwordx4 v[244:247], v[244:245], off offset:256
	s_waitcnt vmcnt(0)
	v_mov_b64_e32 v[138:139], v[212:213]
	v_mov_b64_e32 v[140:141], v[214:215]
	v_mov_b64_e32 v[142:143], v[216:217]
	v_mov_b64_e32 v[144:145], v[218:219]
	s_mov_b32 s0, 0x3a000000
	v_readlane_b32 s4, v255, 27
	v_lshlrev_b64 v[162:163], 2, v[130:131]
	v_readlane_b32 s5, v255, 28
	v_and_b32_e32 v169, 64, v205
	v_xor_b32_e32 v168, 16, v205
	v_add_u32_e32 v169, 64, v169
	v_xor_b32_e32 v170, 32, v205
	v_and_b32_e32 v167, 63, v164
	s_waitcnt vmcnt(0)
	v_cvt_pk_f32_fp8_sdwa v[150:151], v138 src0_sel:WORD_1
	v_cvt_pk_f32_fp8_e32 v[148:149], v138
	v_cvt_pk_f32_fp8_e32 v[152:153], v139
	v_cvt_pk_f32_fp8_sdwa v[138:139], v139 src0_sel:WORD_1
	v_lshlrev_b32_e32 v154, 16, v142
	v_and_b32_e32 v155, 0xffff0000, v142
	v_lshlrev_b32_e32 v142, 16, v143
	v_and_b32_e32 v143, 0xffff0000, v143
	v_pk_fma_f32 v[142:143], v[150:151], s[0:1], v[142:143] op_sel_hi:[1,0,1]
	v_lshlrev_b32_e32 v150, 16, v144
	v_and_b32_e32 v151, 0xffff0000, v144
	v_lshlrev_b32_e32 v144, 16, v145
	v_and_b32_e32 v145, 0xffff0000, v145
	v_pk_fma_f32 v[138:139], v[138:139], s[0:1], v[144:145] op_sel_hi:[1,0,1]
	v_pk_fma_f32 v[8:9], v[142:143], s[86:87], v[8:9] op_sel_hi:[1,0,1]
	s_waitcnt vmcnt(0)
	v_mov_b64_e32 v[142:143], v[220:221]
	v_mov_b64_e32 v[144:145], v[222:223]
	v_pk_fma_f32 v[4:5], v[138:139], s[86:87], v[4:5] op_sel_hi:[1,0,1]
	v_cvt_pk_f32_fp8_e32 v[138:139], v140
	v_pk_fma_f32 v[150:151], v[152:153], s[0:1], v[150:151] op_sel_hi:[1,0,1]
	v_cvt_pk_f32_fp8_sdwa v[146:147], v140 src0_sel:WORD_1
	v_pk_fma_f32 v[148:149], v[148:149], s[0:1], v[154:155] op_sel_hi:[1,0,1]
	v_pk_fma_f32 v[2:3], v[150:151], s[86:87], v[2:3] op_sel_hi:[1,0,1]
	v_pk_fma_f32 v[6:7], v[148:149], s[86:87], v[6:7] op_sel_hi:[1,0,1]
	v_cvt_pk_f32_fp8_e32 v[148:149], v141
	v_cvt_pk_f32_fp8_sdwa v[140:141], v141 src0_sel:WORD_1
	s_waitcnt vmcnt(0)
	v_lshlrev_b32_e32 v150, 16, v142
	v_and_b32_e32 v151, 0xffff0000, v142
	v_pk_fma_f32 v[138:139], v[138:139], s[0:1], v[150:151] op_sel_hi:[1,0,1]
	v_lshlrev_b32_e32 v142, 16, v143
	v_and_b32_e32 v143, 0xffff0000, v143
	v_pk_fma_f32 v[22:23], v[138:139], s[86:87], v[22:23] op_sel_hi:[1,0,1]
	v_or_b32_e32 v138, 16, v136
	v_pk_fma_f32 v[142:143], v[146:147], s[0:1], v[142:143] op_sel_hi:[1,0,1]
	v_ashrrev_i32_e32 v139, 31, v138
	v_lshlrev_b32_e32 v146, 16, v144
	v_and_b32_e32 v147, 0xffff0000, v144
	v_lshlrev_b32_e32 v144, 16, v145
	v_and_b32_e32 v145, 0xffff0000, v145
	v_pk_fma_f32 v[24:25], v[142:143], s[86:87], v[24:25] op_sel_hi:[1,0,1]
	v_lshlrev_b64 v[142:143], 11, v[138:139]
	v_pk_fma_f32 v[146:147], v[148:149], s[0:1], v[146:147] op_sel_hi:[1,0,1]
	v_pk_fma_f32 v[140:141], v[140:141], s[0:1], v[144:145] op_sel_hi:[1,0,1]
	v_lshl_add_u64 v[138:139], s[8:9], 0, v[142:143]
	v_pk_fma_f32 v[20:21], v[140:141], s[86:87], v[20:21] op_sel_hi:[1,0,1]
	v_pk_fma_f32 v[18:19], v[146:147], s[86:87], v[18:19] op_sel_hi:[1,0,1]
	v_lshl_add_u64 v[138:139], v[138:139], 0, v[134:135]
	s_waitcnt vmcnt(0)
	v_mov_b64_e32 v[138:139], v[224:225]
	v_mov_b64_e32 v[140:141], v[226:227]
	v_lshl_add_u64 v[142:143], s[6:7], 0, v[142:143]
	v_lshl_add_u64 v[146:147], v[142:143], 0, v[132:133]
	s_waitcnt vmcnt(0)
	v_mov_b64_e32 v[142:143], v[228:229]
	v_mov_b64_e32 v[144:145], v[230:231]
	v_mov_b32_e32 v171, v8
	v_mov_b32_e32 v172, v6
	v_mov_b32_e32 v173, v9
	v_mov_b32_e32 v174, v2
	v_mov_b32_e32 v175, v5
	v_add_f32_e32 v177, v24, v25
	v_mov_b32_e32 v176, v19
	s_waitcnt vmcnt(1)
	v_cvt_pk_f32_fp8_sdwa v[150:151], v138 src0_sel:WORD_1
	v_cvt_pk_f32_fp8_e32 v[148:149], v138
	v_cvt_pk_f32_fp8_e32 v[152:153], v139
	v_cvt_pk_f32_fp8_sdwa v[138:139], v139 src0_sel:WORD_1
	s_waitcnt vmcnt(0)
	v_lshlrev_b32_e32 v154, 16, v142
	v_and_b32_e32 v155, 0xffff0000, v142
	v_lshlrev_b32_e32 v142, 16, v143
	v_and_b32_e32 v143, 0xffff0000, v143
	v_pk_fma_f32 v[142:143], v[150:151], s[0:1], v[142:143] op_sel_hi:[1,0,1]
	v_lshlrev_b32_e32 v150, 16, v144
	v_and_b32_e32 v151, 0xffff0000, v144
	v_lshlrev_b32_e32 v144, 16, v145
	v_and_b32_e32 v145, 0xffff0000, v145
	v_pk_fma_f32 v[138:139], v[138:139], s[0:1], v[144:145] op_sel_hi:[1,0,1]
	v_pk_fma_f32 v[40:41], v[142:143], s[86:87], v[40:41] op_sel_hi:[1,0,1]
	s_waitcnt vmcnt(0)
	v_mov_b64_e32 v[142:143], v[232:233]
	v_mov_b64_e32 v[144:145], v[234:235]
	v_pk_fma_f32 v[36:37], v[138:139], s[86:87], v[36:37] op_sel_hi:[1,0,1]
	v_cvt_pk_f32_fp8_e32 v[138:139], v140
	v_pk_fma_f32 v[150:151], v[152:153], s[0:1], v[150:151] op_sel_hi:[1,0,1]
	v_cvt_pk_f32_fp8_sdwa v[146:147], v140 src0_sel:WORD_1
	v_pk_fma_f32 v[148:149], v[148:149], s[0:1], v[154:155] op_sel_hi:[1,0,1]
	v_pk_fma_f32 v[34:35], v[150:151], s[86:87], v[34:35] op_sel_hi:[1,0,1]
	v_pk_fma_f32 v[38:39], v[148:149], s[86:87], v[38:39] op_sel_hi:[1,0,1]
	v_cvt_pk_f32_fp8_e32 v[148:149], v141
	v_cvt_pk_f32_fp8_sdwa v[140:141], v141 src0_sel:WORD_1
	s_waitcnt vmcnt(0)
	v_lshlrev_b32_e32 v150, 16, v142
	v_and_b32_e32 v151, 0xffff0000, v142
	v_pk_fma_f32 v[138:139], v[138:139], s[0:1], v[150:151] op_sel_hi:[1,0,1]
	v_lshlrev_b32_e32 v142, 16, v143
	v_and_b32_e32 v143, 0xffff0000, v143
	v_pk_fma_f32 v[46:47], v[138:139], s[86:87], v[46:47] op_sel_hi:[1,0,1]
	v_or_b32_e32 v138, 32, v136
	v_pk_fma_f32 v[142:143], v[146:147], s[0:1], v[142:143] op_sel_hi:[1,0,1]
	v_ashrrev_i32_e32 v139, 31, v138
	v_lshlrev_b32_e32 v146, 16, v144
	v_and_b32_e32 v147, 0xffff0000, v144
	v_lshlrev_b32_e32 v144, 16, v145
	v_and_b32_e32 v145, 0xffff0000, v145
	v_pk_fma_f32 v[48:49], v[142:143], s[86:87], v[48:49] op_sel_hi:[1,0,1]
	v_lshlrev_b64 v[142:143], 11, v[138:139]
	v_pk_fma_f32 v[146:147], v[148:149], s[0:1], v[146:147] op_sel_hi:[1,0,1]
	v_pk_fma_f32 v[140:141], v[140:141], s[0:1], v[144:145] op_sel_hi:[1,0,1]
	v_lshl_add_u64 v[138:139], s[8:9], 0, v[142:143]
	v_pk_fma_f32 v[44:45], v[140:141], s[86:87], v[44:45] op_sel_hi:[1,0,1]
	v_pk_fma_f32 v[42:43], v[146:147], s[86:87], v[42:43] op_sel_hi:[1,0,1]
	v_lshl_add_u64 v[138:139], v[138:139], 0, v[134:135]
	s_waitcnt vmcnt(0)
	v_mov_b64_e32 v[138:139], v[236:237]
	v_mov_b64_e32 v[140:141], v[238:239]
	v_lshl_add_u64 v[142:143], s[6:7], 0, v[142:143]
	v_lshl_add_u64 v[146:147], v[142:143], 0, v[132:133]
	s_waitcnt vmcnt(0)
	v_mov_b64_e32 v[142:143], v[240:241]
	v_mov_b64_e32 v[144:145], v[242:243]
	s_waitcnt vmcnt(1)
	v_cvt_pk_f32_fp8_sdwa v[150:151], v138 src0_sel:WORD_1
	v_cvt_pk_f32_fp8_e32 v[148:149], v138
	v_cvt_pk_f32_fp8_e32 v[152:153], v139
	v_cvt_pk_f32_fp8_sdwa v[138:139], v139 src0_sel:WORD_1
	s_waitcnt vmcnt(0)
	v_lshlrev_b32_e32 v154, 16, v142
	v_and_b32_e32 v155, 0xffff0000, v142
	v_lshlrev_b32_e32 v142, 16, v143
	v_and_b32_e32 v143, 0xffff0000, v143
	v_pk_fma_f32 v[142:143], v[150:151], s[0:1], v[142:143] op_sel_hi:[1,0,1]
	v_lshlrev_b32_e32 v150, 16, v144
	v_and_b32_e32 v151, 0xffff0000, v144
	v_lshlrev_b32_e32 v144, 16, v145
	v_and_b32_e32 v145, 0xffff0000, v145
	v_pk_fma_f32 v[138:139], v[138:139], s[0:1], v[144:145] op_sel_hi:[1,0,1]
	v_pk_fma_f32 v[64:65], v[142:143], s[86:87], v[64:65] op_sel_hi:[1,0,1]
	s_waitcnt vmcnt(0)
	v_mov_b64_e32 v[142:143], v[244:245]
	v_mov_b64_e32 v[144:145], v[246:247]
	s_mov_b32 s98, 0x18000
	s_mov_b32 s99, 0
	v_lshl_add_u64 v[212:213], v[248:249], 0, s[98:99]
	global_load_dwordx4 v[212:215], v[212:213], off
	s_mov_b32 s98, 0x18000
	s_mov_b32 s99, 0
	v_lshl_add_u64 v[216:217], v[250:251], 0, s[98:99]
	global_load_dwordx4 v[216:219], v[216:217], off
	s_mov_b32 s98, 0x18000
	s_mov_b32 s99, 0
	v_lshl_add_u64 v[220:221], v[250:251], 0, s[98:99]
	global_load_dwordx4 v[220:223], v[220:221], off offset:256
	s_mov_b32 s98, 0x40000
	s_mov_b32 s99, 0
	v_lshl_add_u64 v[224:225], v[248:249], 0, s[98:99]
	global_load_dwordx4 v[224:227], v[224:225], off
	s_mov_b32 s98, 0x40000
	s_mov_b32 s99, 0
	v_lshl_add_u64 v[228:229], v[250:251], 0, s[98:99]
	global_load_dwordx4 v[228:231], v[228:229], off
	s_mov_b32 s98, 0x40000
	s_mov_b32 s99, 0
	v_lshl_add_u64 v[232:233], v[250:251], 0, s[98:99]
	global_load_dwordx4 v[232:235], v[232:233], off offset:256
	s_mov_b32 s98, 0x48000
	s_mov_b32 s99, 0
	v_lshl_add_u64 v[236:237], v[248:249], 0, s[98:99]
	global_load_dwordx4 v[236:239], v[236:237], off
	s_mov_b32 s98, 0x48000
	s_mov_b32 s99, 0
	v_lshl_add_u64 v[240:241], v[250:251], 0, s[98:99]
	global_load_dwordx4 v[240:243], v[240:241], off
	s_mov_b32 s98, 0x48000
	s_mov_b32 s99, 0
	v_lshl_add_u64 v[244:245], v[250:251], 0, s[98:99]
	global_load_dwordx4 v[244:247], v[244:245], off offset:256
	v_pk_fma_f32 v[60:61], v[138:139], s[86:87], v[60:61] op_sel_hi:[1,0,1]
	v_cvt_pk_f32_fp8_e32 v[138:139], v140
	v_pk_fma_f32 v[150:151], v[152:153], s[0:1], v[150:151] op_sel_hi:[1,0,1]
	v_cvt_pk_f32_fp8_sdwa v[146:147], v140 src0_sel:WORD_1
	v_pk_fma_f32 v[148:149], v[148:149], s[0:1], v[154:155] op_sel_hi:[1,0,1]
	v_pk_fma_f32 v[58:59], v[150:151], s[86:87], v[58:59] op_sel_hi:[1,0,1]
	v_pk_fma_f32 v[62:63], v[148:149], s[86:87], v[62:63] op_sel_hi:[1,0,1]
	v_cvt_pk_f32_fp8_e32 v[148:149], v141
	v_cvt_pk_f32_fp8_sdwa v[140:141], v141 src0_sel:WORD_1
	s_waitcnt vmcnt(0)
	v_lshlrev_b32_e32 v150, 16, v142
	v_and_b32_e32 v151, 0xffff0000, v142
	v_pk_fma_f32 v[138:139], v[138:139], s[0:1], v[150:151] op_sel_hi:[1,0,1]
	v_lshlrev_b32_e32 v142, 16, v143
	v_and_b32_e32 v143, 0xffff0000, v143
	v_pk_fma_f32 v[78:79], v[138:139], s[86:87], v[78:79] op_sel_hi:[1,0,1]
	v_or_b32_e32 v138, 48, v136
	v_pk_fma_f32 v[142:143], v[146:147], s[0:1], v[142:143] op_sel_hi:[1,0,1]
	v_ashrrev_i32_e32 v139, 31, v138
	v_lshlrev_b32_e32 v146, 16, v144
	v_and_b32_e32 v147, 0xffff0000, v144
	v_lshlrev_b32_e32 v144, 16, v145
	v_and_b32_e32 v145, 0xffff0000, v145
	v_pk_fma_f32 v[80:81], v[142:143], s[86:87], v[80:81] op_sel_hi:[1,0,1]
	v_lshlrev_b64 v[142:143], 11, v[138:139]
	v_pk_fma_f32 v[146:147], v[148:149], s[0:1], v[146:147] op_sel_hi:[1,0,1]
	v_pk_fma_f32 v[140:141], v[140:141], s[0:1], v[144:145] op_sel_hi:[1,0,1]
	v_lshl_add_u64 v[138:139], s[8:9], 0, v[142:143]
	v_pk_fma_f32 v[76:77], v[140:141], s[86:87], v[76:77] op_sel_hi:[1,0,1]
	v_pk_fma_f32 v[74:75], v[146:147], s[86:87], v[74:75] op_sel_hi:[1,0,1]
	v_lshl_add_u64 v[138:139], v[138:139], 0, v[134:135]
	s_waitcnt vmcnt(0)
	v_mov_b64_e32 v[138:139], v[212:213]
	v_mov_b64_e32 v[140:141], v[214:215]
	v_lshl_add_u64 v[142:143], s[6:7], 0, v[142:143]
	v_lshl_add_u64 v[146:147], v[142:143], 0, v[132:133]
	s_waitcnt vmcnt(0)
	v_mov_b64_e32 v[142:143], v[216:217]
	v_mov_b64_e32 v[144:145], v[218:219]
	s_waitcnt vmcnt(1)
	v_cvt_pk_f32_fp8_sdwa v[150:151], v138 src0_sel:WORD_1
	v_cvt_pk_f32_fp8_e32 v[148:149], v138
	v_cvt_pk_f32_fp8_e32 v[152:153], v139
	v_cvt_pk_f32_fp8_sdwa v[138:139], v139 src0_sel:WORD_1
	s_waitcnt vmcnt(0)
	v_lshlrev_b32_e32 v154, 16, v142
	v_and_b32_e32 v155, 0xffff0000, v142
	v_lshlrev_b32_e32 v142, 16, v143
	v_and_b32_e32 v143, 0xffff0000, v143
	v_pk_fma_f32 v[142:143], v[150:151], s[0:1], v[142:143] op_sel_hi:[1,0,1]
	v_lshlrev_b32_e32 v150, 16, v144
	v_and_b32_e32 v151, 0xffff0000, v144
	v_lshlrev_b32_e32 v144, 16, v145
	v_and_b32_e32 v145, 0xffff0000, v145
	v_pk_fma_f32 v[138:139], v[138:139], s[0:1], v[144:145] op_sel_hi:[1,0,1]
	v_pk_fma_f32 v[96:97], v[142:143], s[86:87], v[96:97] op_sel_hi:[1,0,1]
	s_waitcnt vmcnt(0)
	v_mov_b64_e32 v[142:143], v[220:221]
	v_mov_b64_e32 v[144:145], v[222:223]
	v_pk_fma_f32 v[92:93], v[138:139], s[86:87], v[92:93] op_sel_hi:[1,0,1]
	v_cvt_pk_f32_fp8_e32 v[138:139], v140
	v_pk_fma_f32 v[150:151], v[152:153], s[0:1], v[150:151] op_sel_hi:[1,0,1]
	v_cvt_pk_f32_fp8_sdwa v[146:147], v140 src0_sel:WORD_1
	v_pk_fma_f32 v[148:149], v[148:149], s[0:1], v[154:155] op_sel_hi:[1,0,1]
	v_pk_fma_f32 v[90:91], v[150:151], s[86:87], v[90:91] op_sel_hi:[1,0,1]
	v_pk_fma_f32 v[94:95], v[148:149], s[86:87], v[94:95] op_sel_hi:[1,0,1]
	v_cvt_pk_f32_fp8_e32 v[148:149], v141
	v_cvt_pk_f32_fp8_sdwa v[140:141], v141 src0_sel:WORD_1
	s_waitcnt vmcnt(0)
	v_lshlrev_b32_e32 v150, 16, v142
	v_and_b32_e32 v151, 0xffff0000, v142
	v_pk_fma_f32 v[138:139], v[138:139], s[0:1], v[150:151] op_sel_hi:[1,0,1]
	v_lshlrev_b32_e32 v142, 16, v143
	v_and_b32_e32 v143, 0xffff0000, v143
	v_pk_fma_f32 v[102:103], v[138:139], s[86:87], v[102:103] op_sel_hi:[1,0,1]
	v_add_u32_e32 v138, 0x80, v136
	v_pk_fma_f32 v[142:143], v[146:147], s[0:1], v[142:143] op_sel_hi:[1,0,1]
	v_ashrrev_i32_e32 v139, 31, v138
	v_lshlrev_b32_e32 v146, 16, v144
	v_and_b32_e32 v147, 0xffff0000, v144
	v_lshlrev_b32_e32 v144, 16, v145
	v_and_b32_e32 v145, 0xffff0000, v145
	v_pk_fma_f32 v[104:105], v[142:143], s[86:87], v[104:105] op_sel_hi:[1,0,1]
	v_lshlrev_b64 v[142:143], 11, v[138:139]
	v_pk_fma_f32 v[146:147], v[148:149], s[0:1], v[146:147] op_sel_hi:[1,0,1]
	v_pk_fma_f32 v[140:141], v[140:141], s[0:1], v[144:145] op_sel_hi:[1,0,1]
	v_lshl_add_u64 v[138:139], s[8:9], 0, v[142:143]
	v_pk_fma_f32 v[100:101], v[140:141], s[86:87], v[100:101] op_sel_hi:[1,0,1]
	v_pk_fma_f32 v[98:99], v[146:147], s[86:87], v[98:99] op_sel_hi:[1,0,1]
	v_lshl_add_u64 v[138:139], v[138:139], 0, v[134:135]
	s_waitcnt vmcnt(0)
	v_mov_b64_e32 v[138:139], v[224:225]
	v_mov_b64_e32 v[140:141], v[226:227]
	v_lshl_add_u64 v[142:143], s[6:7], 0, v[142:143]
	v_lshl_add_u64 v[146:147], v[142:143], 0, v[132:133]
	s_waitcnt vmcnt(0)
	v_mov_b64_e32 v[142:143], v[228:229]
	v_mov_b64_e32 v[144:145], v[230:231]
	s_waitcnt vmcnt(1)
	v_cvt_pk_f32_fp8_sdwa v[150:151], v138 src0_sel:WORD_1
	v_cvt_pk_f32_fp8_e32 v[148:149], v138
	v_cvt_pk_f32_fp8_e32 v[152:153], v139
	v_cvt_pk_f32_fp8_sdwa v[138:139], v139 src0_sel:WORD_1
	s_waitcnt vmcnt(0)
	v_lshlrev_b32_e32 v154, 16, v142
	v_and_b32_e32 v155, 0xffff0000, v142
	v_lshlrev_b32_e32 v142, 16, v143
	v_and_b32_e32 v143, 0xffff0000, v143
	v_pk_fma_f32 v[142:143], v[150:151], s[0:1], v[142:143] op_sel_hi:[1,0,1]
	v_lshlrev_b32_e32 v150, 16, v144
	v_and_b32_e32 v151, 0xffff0000, v144
	v_lshlrev_b32_e32 v144, 16, v145
	v_and_b32_e32 v145, 0xffff0000, v145
	v_pk_fma_f32 v[138:139], v[138:139], s[0:1], v[144:145] op_sel_hi:[1,0,1]
	v_pk_fma_f32 v[120:121], v[142:143], s[86:87], v[120:121] op_sel_hi:[1,0,1]
	s_waitcnt vmcnt(0)
	v_mov_b64_e32 v[142:143], v[232:233]
	v_mov_b64_e32 v[144:145], v[234:235]
	v_pk_fma_f32 v[116:117], v[138:139], s[86:87], v[116:117] op_sel_hi:[1,0,1]
	v_cvt_pk_f32_fp8_e32 v[138:139], v140
	v_pk_fma_f32 v[150:151], v[152:153], s[0:1], v[150:151] op_sel_hi:[1,0,1]
	v_cvt_pk_f32_fp8_sdwa v[146:147], v140 src0_sel:WORD_1
	v_pk_fma_f32 v[148:149], v[148:149], s[0:1], v[154:155] op_sel_hi:[1,0,1]
	v_pk_fma_f32 v[114:115], v[150:151], s[86:87], v[114:115] op_sel_hi:[1,0,1]
	v_pk_fma_f32 v[118:119], v[148:149], s[86:87], v[118:119] op_sel_hi:[1,0,1]
	v_cvt_pk_f32_fp8_e32 v[148:149], v141
	v_cvt_pk_f32_fp8_sdwa v[140:141], v141 src0_sel:WORD_1
	s_waitcnt vmcnt(0)
	v_lshlrev_b32_e32 v150, 16, v142
	v_and_b32_e32 v151, 0xffff0000, v142
	v_pk_fma_f32 v[138:139], v[138:139], s[0:1], v[150:151] op_sel_hi:[1,0,1]
	v_lshlrev_b32_e32 v142, 16, v143
	v_and_b32_e32 v143, 0xffff0000, v143
	v_pk_fma_f32 v[126:127], v[138:139], s[86:87], v[126:127] op_sel_hi:[1,0,1]
	v_add_u32_e32 v138, 0x90, v136
	v_pk_fma_f32 v[142:143], v[146:147], s[0:1], v[142:143] op_sel_hi:[1,0,1]
	v_ashrrev_i32_e32 v139, 31, v138
	v_lshlrev_b32_e32 v146, 16, v144
	v_and_b32_e32 v147, 0xffff0000, v144
	v_lshlrev_b32_e32 v144, 16, v145
	v_and_b32_e32 v145, 0xffff0000, v145
	v_pk_fma_f32 v[128:129], v[142:143], s[86:87], v[128:129] op_sel_hi:[1,0,1]
	v_lshlrev_b64 v[142:143], 11, v[138:139]
	v_pk_fma_f32 v[146:147], v[148:149], s[0:1], v[146:147] op_sel_hi:[1,0,1]
	v_pk_fma_f32 v[140:141], v[140:141], s[0:1], v[144:145] op_sel_hi:[1,0,1]
	v_lshl_add_u64 v[138:139], s[8:9], 0, v[142:143]
	v_pk_fma_f32 v[124:125], v[140:141], s[86:87], v[124:125] op_sel_hi:[1,0,1]
	v_pk_fma_f32 v[122:123], v[146:147], s[86:87], v[122:123] op_sel_hi:[1,0,1]
	v_lshl_add_u64 v[138:139], v[138:139], 0, v[134:135]
	s_waitcnt vmcnt(0)
	v_mov_b64_e32 v[138:139], v[236:237]
	v_mov_b64_e32 v[140:141], v[238:239]
	v_lshl_add_u64 v[142:143], s[6:7], 0, v[142:143]
	v_lshl_add_u64 v[146:147], v[142:143], 0, v[132:133]
	s_waitcnt vmcnt(0)
	v_mov_b64_e32 v[142:143], v[240:241]
	v_mov_b64_e32 v[144:145], v[242:243]
	s_waitcnt vmcnt(1)
	v_cvt_pk_f32_fp8_sdwa v[150:151], v138 src0_sel:WORD_1
	v_cvt_pk_f32_fp8_e32 v[148:149], v138
	v_cvt_pk_f32_fp8_e32 v[152:153], v139
	v_cvt_pk_f32_fp8_sdwa v[138:139], v139 src0_sel:WORD_1
	s_waitcnt vmcnt(0)
	v_lshlrev_b32_e32 v154, 16, v142
	v_and_b32_e32 v155, 0xffff0000, v142
	v_lshlrev_b32_e32 v142, 16, v143
	v_and_b32_e32 v143, 0xffff0000, v143
	v_pk_fma_f32 v[142:143], v[150:151], s[0:1], v[142:143] op_sel_hi:[1,0,1]
	v_lshlrev_b32_e32 v150, 16, v144
	v_and_b32_e32 v151, 0xffff0000, v144
	v_lshlrev_b32_e32 v144, 16, v145
	v_and_b32_e32 v145, 0xffff0000, v145
	v_pk_fma_f32 v[138:139], v[138:139], s[0:1], v[144:145] op_sel_hi:[1,0,1]
	v_pk_fma_f32 v[112:113], v[142:143], s[86:87], v[112:113] op_sel_hi:[1,0,1]
	s_waitcnt vmcnt(0)
	v_mov_b64_e32 v[142:143], v[244:245]
	v_mov_b64_e32 v[144:145], v[246:247]
	s_mov_b32 s98, 0x50000
	s_mov_b32 s99, 0
	v_lshl_add_u64 v[212:213], v[248:249], 0, s[98:99]
	global_load_dwordx4 v[212:215], v[212:213], off
	s_mov_b32 s98, 0x50000
	s_mov_b32 s99, 0
	v_lshl_add_u64 v[216:217], v[250:251], 0, s[98:99]
	global_load_dwordx4 v[216:219], v[216:217], off
	s_mov_b32 s98, 0x50000
	s_mov_b32 s99, 0
	v_lshl_add_u64 v[220:221], v[250:251], 0, s[98:99]
	global_load_dwordx4 v[220:223], v[220:221], off offset:256
	s_mov_b32 s98, 0x58000
	s_mov_b32 s99, 0
	v_lshl_add_u64 v[224:225], v[248:249], 0, s[98:99]
	global_load_dwordx4 v[224:227], v[224:225], off
	s_mov_b32 s98, 0x58000
	s_mov_b32 s99, 0
	v_lshl_add_u64 v[228:229], v[250:251], 0, s[98:99]
	global_load_dwordx4 v[228:231], v[228:229], off
	s_mov_b32 s98, 0x58000
	s_mov_b32 s99, 0
	v_lshl_add_u64 v[232:233], v[250:251], 0, s[98:99]
	global_load_dwordx4 v[232:235], v[232:233], off offset:256
	v_pk_fma_f32 v[108:109], v[138:139], s[86:87], v[108:109] op_sel_hi:[1,0,1]
	v_cvt_pk_f32_fp8_e32 v[138:139], v140
	v_pk_fma_f32 v[150:151], v[152:153], s[0:1], v[150:151] op_sel_hi:[1,0,1]
	v_cvt_pk_f32_fp8_sdwa v[146:147], v140 src0_sel:WORD_1
	v_pk_fma_f32 v[148:149], v[148:149], s[0:1], v[154:155] op_sel_hi:[1,0,1]
	v_pk_fma_f32 v[106:107], v[150:151], s[86:87], v[106:107] op_sel_hi:[1,0,1]
	v_pk_fma_f32 v[110:111], v[148:149], s[86:87], v[110:111] op_sel_hi:[1,0,1]
	v_cvt_pk_f32_fp8_e32 v[148:149], v141
	v_cvt_pk_f32_fp8_sdwa v[140:141], v141 src0_sel:WORD_1
	s_waitcnt vmcnt(0)
	v_lshlrev_b32_e32 v150, 16, v142
	v_and_b32_e32 v151, 0xffff0000, v142
	v_pk_fma_f32 v[138:139], v[138:139], s[0:1], v[150:151] op_sel_hi:[1,0,1]
	v_lshlrev_b32_e32 v142, 16, v143
	v_and_b32_e32 v143, 0xffff0000, v143
	v_pk_fma_f32 v[86:87], v[138:139], s[86:87], v[86:87] op_sel_hi:[1,0,1]
	v_add_u32_e32 v138, 0xa0, v136
	v_pk_fma_f32 v[142:143], v[146:147], s[0:1], v[142:143] op_sel_hi:[1,0,1]
	v_ashrrev_i32_e32 v139, 31, v138
	v_lshlrev_b32_e32 v146, 16, v144
	v_and_b32_e32 v147, 0xffff0000, v144
	v_lshlrev_b32_e32 v144, 16, v145
	v_and_b32_e32 v145, 0xffff0000, v145
	v_pk_fma_f32 v[88:89], v[142:143], s[86:87], v[88:89] op_sel_hi:[1,0,1]
	v_lshlrev_b64 v[142:143], 11, v[138:139]
	v_pk_fma_f32 v[146:147], v[148:149], s[0:1], v[146:147] op_sel_hi:[1,0,1]
	v_pk_fma_f32 v[140:141], v[140:141], s[0:1], v[144:145] op_sel_hi:[1,0,1]
	v_lshl_add_u64 v[138:139], s[8:9], 0, v[142:143]
	v_pk_fma_f32 v[84:85], v[140:141], s[86:87], v[84:85] op_sel_hi:[1,0,1]
	v_pk_fma_f32 v[82:83], v[146:147], s[86:87], v[82:83] op_sel_hi:[1,0,1]
	v_lshl_add_u64 v[138:139], v[138:139], 0, v[134:135]
	s_waitcnt vmcnt(0)
	v_mov_b64_e32 v[138:139], v[212:213]
	v_mov_b64_e32 v[140:141], v[214:215]
	v_lshl_add_u64 v[142:143], s[6:7], 0, v[142:143]
	v_lshl_add_u64 v[146:147], v[142:143], 0, v[132:133]
	s_waitcnt vmcnt(0)
	v_mov_b64_e32 v[142:143], v[216:217]
	v_mov_b64_e32 v[144:145], v[218:219]
	v_add_u32_e32 v136, 0xb0, v136
	v_ashrrev_i32_e32 v137, 31, v136
	s_waitcnt vmcnt(1)
	v_cvt_pk_f32_fp8_sdwa v[150:151], v138 src0_sel:WORD_1
	v_cvt_pk_f32_fp8_e32 v[148:149], v138
	v_cvt_pk_f32_fp8_e32 v[152:153], v139
	v_cvt_pk_f32_fp8_sdwa v[138:139], v139 src0_sel:WORD_1
	s_waitcnt vmcnt(0)
	v_lshlrev_b32_e32 v154, 16, v142
	v_and_b32_e32 v155, 0xffff0000, v142
	v_lshlrev_b32_e32 v142, 16, v143
	v_and_b32_e32 v143, 0xffff0000, v143
	v_pk_fma_f32 v[142:143], v[150:151], s[0:1], v[142:143] op_sel_hi:[1,0,1]
	v_lshlrev_b32_e32 v150, 16, v144
	v_and_b32_e32 v151, 0xffff0000, v144
	v_lshlrev_b32_e32 v144, 16, v145
	v_and_b32_e32 v145, 0xffff0000, v145
	v_pk_fma_f32 v[138:139], v[138:139], s[0:1], v[144:145] op_sel_hi:[1,0,1]
	v_pk_fma_f32 v[72:73], v[142:143], s[86:87], v[72:73] op_sel_hi:[1,0,1]
	s_waitcnt vmcnt(0)
	v_mov_b64_e32 v[142:143], v[220:221]
	v_mov_b64_e32 v[144:145], v[222:223]
	v_pk_fma_f32 v[68:69], v[138:139], s[86:87], v[68:69] op_sel_hi:[1,0,1]
	v_cvt_pk_f32_fp8_e32 v[138:139], v140
	v_pk_fma_f32 v[148:149], v[148:149], s[0:1], v[154:155] op_sel_hi:[1,0,1]
	v_cvt_pk_f32_fp8_sdwa v[146:147], v140 src0_sel:WORD_1
	v_pk_fma_f32 v[150:151], v[152:153], s[0:1], v[150:151] op_sel_hi:[1,0,1]
	v_pk_fma_f32 v[70:71], v[148:149], s[86:87], v[70:71] op_sel_hi:[1,0,1]
	v_cvt_pk_f32_fp8_e32 v[148:149], v141
	v_cvt_pk_f32_fp8_sdwa v[140:141], v141 src0_sel:WORD_1
	v_pk_fma_f32 v[66:67], v[150:151], s[86:87], v[66:67] op_sel_hi:[1,0,1]
	s_waitcnt vmcnt(0)
	v_lshlrev_b32_e32 v150, 16, v142
	v_and_b32_e32 v151, 0xffff0000, v142
	v_pk_fma_f32 v[138:139], v[138:139], s[0:1], v[150:151] op_sel_hi:[1,0,1]
	v_lshlrev_b32_e32 v142, 16, v143
	v_and_b32_e32 v143, 0xffff0000, v143
	v_pk_fma_f32 v[142:143], v[146:147], s[0:1], v[142:143] op_sel_hi:[1,0,1]
	v_lshlrev_b32_e32 v146, 16, v144
	v_and_b32_e32 v147, 0xffff0000, v144
	v_lshlrev_b32_e32 v144, 16, v145
	v_and_b32_e32 v145, 0xffff0000, v145
	v_pk_fma_f32 v[54:55], v[138:139], s[86:87], v[54:55] op_sel_hi:[1,0,1]
	v_lshlrev_b64 v[138:139], 11, v[136:137]
	v_pk_fma_f32 v[146:147], v[148:149], s[0:1], v[146:147] op_sel_hi:[1,0,1]
	v_pk_fma_f32 v[140:141], v[140:141], s[0:1], v[144:145] op_sel_hi:[1,0,1]
	v_lshl_add_u64 v[136:137], s[8:9], 0, v[138:139]
	v_pk_fma_f32 v[56:57], v[142:143], s[86:87], v[56:57] op_sel_hi:[1,0,1]
	v_pk_fma_f32 v[52:53], v[140:141], s[86:87], v[52:53] op_sel_hi:[1,0,1]
	v_pk_fma_f32 v[50:51], v[146:147], s[86:87], v[50:51] op_sel_hi:[1,0,1]
	v_lshl_add_u64 v[134:135], v[136:137], 0, v[134:135]
	s_waitcnt vmcnt(0)
	v_mov_b64_e32 v[134:135], v[224:225]
	v_mov_b64_e32 v[136:137], v[226:227]
	v_lshl_add_u64 v[138:139], s[6:7], 0, v[138:139]
	v_lshl_add_u64 v[132:133], v[138:139], 0, v[132:133]
	s_waitcnt vmcnt(0)
	v_mov_b64_e32 v[138:139], v[228:229]
	v_mov_b64_e32 v[140:141], v[230:231]
	s_waitcnt vmcnt(1)
	v_cvt_pk_f32_fp8_sdwa v[144:145], v134 src0_sel:WORD_1
	v_cvt_pk_f32_fp8_e32 v[142:143], v134
	v_cvt_pk_f32_fp8_e32 v[146:147], v135
	v_cvt_pk_f32_fp8_sdwa v[134:135], v135 src0_sel:WORD_1
	s_waitcnt vmcnt(0)
	v_lshlrev_b32_e32 v148, 16, v138
	v_and_b32_e32 v149, 0xffff0000, v138
	v_lshlrev_b32_e32 v138, 16, v139
	v_and_b32_e32 v139, 0xffff0000, v139
	v_pk_fma_f32 v[138:139], v[144:145], s[0:1], v[138:139] op_sel_hi:[1,0,1]
	v_lshlrev_b32_e32 v144, 16, v140
	v_and_b32_e32 v145, 0xffff0000, v140
	v_lshlrev_b32_e32 v140, 16, v141
	v_and_b32_e32 v141, 0xffff0000, v141
	v_pk_fma_f32 v[134:135], v[134:135], s[0:1], v[140:141] op_sel_hi:[1,0,1]
	v_pk_fma_f32 v[142:143], v[142:143], s[0:1], v[148:149] op_sel_hi:[1,0,1]
	v_pk_fma_f32 v[28:29], v[134:135], s[86:87], v[28:29] op_sel_hi:[1,0,1]
	s_waitcnt vmcnt(0)
	v_mov_b64_e32 v[132:133], v[232:233]
	v_mov_b64_e32 v[134:135], v[234:235]
	v_cvt_pk_f32_fp8_sdwa v[140:141], v136 src0_sel:WORD_1
	v_pk_fma_f32 v[32:33], v[138:139], s[86:87], v[32:33] op_sel_hi:[1,0,1]
	v_pk_fma_f32 v[30:31], v[142:143], s[86:87], v[30:31] op_sel_hi:[1,0,1]
	v_cvt_pk_f32_fp8_e32 v[138:139], v136
	v_cvt_pk_f32_fp8_e32 v[142:143], v137
	v_cvt_pk_f32_fp8_sdwa v[136:137], v137 src0_sel:WORD_1
	v_pk_fma_f32 v[144:145], v[146:147], s[0:1], v[144:145] op_sel_hi:[1,0,1]
	s_nop 0
	v_pk_fma_f32 v[26:27], v[144:145], s[86:87], v[26:27] op_sel_hi:[1,0,1]
	s_waitcnt vmcnt(0)
	v_lshlrev_b32_e32 v144, 16, v132
	v_and_b32_e32 v145, 0xffff0000, v132
	v_lshlrev_b32_e32 v132, 16, v133
	v_and_b32_e32 v133, 0xffff0000, v133
	v_pk_fma_f32 v[132:133], v[140:141], s[0:1], v[132:133] op_sel_hi:[1,0,1]
	v_lshlrev_b32_e32 v140, 16, v134
	v_and_b32_e32 v141, 0xffff0000, v134
	v_lshlrev_b32_e32 v134, 16, v135
	v_and_b32_e32 v135, 0xffff0000, v135
	v_pk_fma_f32 v[138:139], v[138:139], s[0:1], v[144:145] op_sel_hi:[1,0,1]
	v_pk_fma_f32 v[140:141], v[142:143], s[0:1], v[140:141] op_sel_hi:[1,0,1]
	v_pk_fma_f32 v[134:135], v[136:137], s[0:1], v[134:135] op_sel_hi:[1,0,1]
	v_readlane_b32 s0, v255, 18
	v_readlane_b32 s1, v255, 19
	v_pk_fma_f32 v[16:17], v[132:133], s[86:87], v[16:17] op_sel_hi:[1,0,1]
	v_lshl_add_u64 v[132:133], s[4:5], 0, v[162:163]
	v_lshl_add_u64 v[130:131], s[0:1], 0, v[162:163]
	s_mov_b64 s[0:1], 0x2000
	v_pk_fma_f32 v[12:13], v[134:135], s[86:87], v[12:13] op_sel_hi:[1,0,1]
	v_lshl_add_u64 v[134:135], v[130:131], 0, s[0:1]
	v_lshl_add_u64 v[142:143], v[132:133], 0, s[0:1]
	s_movk_i32 s0, 0x2000
	v_add_co_u32_e32 v130, vcc, s0, v130
	v_pk_fma_f32 v[14:15], v[138:139], s[86:87], v[14:15] op_sel_hi:[1,0,1]
	v_pk_fma_f32 v[10:11], v[140:141], s[86:87], v[10:11] op_sel_hi:[1,0,1]
	v_addc_co_u32_e32 v131, vcc, 0, v131, vcc
	global_load_dwordx4 v[154:157], v[130:131], off
	global_load_dwordx4 v[146:149], v[134:135], off offset:16
	v_add_co_u32_e32 v130, vcc, s0, v132
	s_lshl_b32 s0, s38, 3
	s_nop 0
	v_addc_co_u32_e32 v131, vcc, 0, v133, vcc
	global_load_dwordx4 v[158:161], v[130:131], off
	global_load_dwordx4 v[150:153], v[142:143], off offset:16
	s_nop 0
	global_load_dwordx4 v[130:133], v[134:135], off offset:528
	global_load_dwordx4 v[138:141], v[134:135], off offset:512
	s_nop 0
	global_load_dwordx4 v[134:137], v[142:143], off offset:528
	s_nop 0
	global_load_dwordx4 v[142:145], v[142:143], off offset:512
	v_cmp_lt_i32_e32 vcc, v168, v169
	s_add_i32 s4, s0, 0
	s_nop 0
	v_cndmask_b32_e32 v168, v205, v168, vcc
	v_cmp_lt_i32_e32 vcc, v170, v169
	v_lshlrev_b32_e32 v168, 2, v168
	s_nop 0
	v_cndmask_b32_e32 v169, v205, v170, vcc
	v_mov_b32_e32 v170, v7
	v_pk_add_f32 v[170:171], v[170:171], v[172:173]
	v_mov_b32_e32 v172, v3
	v_mov_b32_e32 v173, v4
	v_pk_add_f32 v[172:173], v[172:173], v[174:175]
	v_add_f32_e32 v170, v170, v171
	v_pk_add_f32 v[172:173], v[172:173], v[172:173] op_sel_hi:[0,1]
	v_add_f32_e32 v171, 0, v170
	v_add_f32_e32 v175, v22, v23
	v_mov_b32_e32 v174, v18
	v_mov_b32_e32 v172, v20
	v_mov_b32_e32 v170, v21
	v_pk_add_f32 v[174:175], v[174:175], v[176:177]
	v_pk_add_f32 v[170:171], v[172:173], v[170:171]
	v_lshlrev_b32_e32 v169, 2, v169
	v_pk_add_f32 v[170:171], v[174:175], v[170:171]
	v_cmp_gt_u32_e32 vcc, 16, v167
	v_add_f32_e32 v170, v170, v171
	ds_bpermute_b32 v171, v168, v170
	s_waitcnt lgkmcnt(0)
	v_add_f32_e32 v170, v170, v171
	ds_bpermute_b32 v171, v169, v170
	s_waitcnt lgkmcnt(0)
	v_add_f32_e32 v170, v170, v171
	v_fmamk_f32 v172, v170, 0xbc800000, v9
	v_fmamk_f32 v174, v170, 0xbc800000, v7
	v_fmamk_f32 v171, v170, 0xbc800000, v8
	v_fmamk_f32 v173, v170, 0xbc800000, v6
	v_mul_f32_e32 v174, v174, v174
	v_mul_f32_e32 v172, v172, v172
	v_fmac_f32_e32 v174, v173, v173
	v_fmac_f32_e32 v172, v171, v171
	v_fmamk_f32 v173, v170, 0xbc800000, v5
	v_fmamk_f32 v175, v170, 0xbc800000, v3
	v_add_f32_e32 v171, v174, v172
	v_fmamk_f32 v172, v170, 0xbc800000, v4
	v_fmamk_f32 v174, v170, 0xbc800000, v2
	v_mul_f32_e32 v175, v175, v175
	v_mul_f32_e32 v173, v173, v173
	v_fmac_f32_e32 v175, v174, v174
	v_fmac_f32_e32 v173, v172, v172
	v_add_f32_e32 v172, v175, v173
	v_fmamk_f32 v173, v170, 0xbc800000, v25
	v_fmamk_f32 v175, v170, 0xbc800000, v23
	v_add_f32_e32 v171, v171, v172
	v_fmamk_f32 v172, v170, 0xbc800000, v24
	v_fmamk_f32 v174, v170, 0xbc800000, v22
	v_mul_f32_e32 v175, v175, v175
	v_mul_f32_e32 v173, v173, v173
	v_fmac_f32_e32 v175, v174, v174
	v_fmac_f32_e32 v173, v172, v172
	v_add_f32_e32 v172, v175, v173
	v_fmamk_f32 v173, v170, 0xbc800000, v21
	v_fmamk_f32 v175, v170, 0xbc800000, v19
	v_add_f32_e32 v171, v172, v171
	v_fmamk_f32 v172, v170, 0xbc800000, v20
	v_fmamk_f32 v174, v170, 0xbc800000, v18
	v_mul_f32_e32 v175, v175, v175
	v_mul_f32_e32 v173, v173, v173
	v_fmac_f32_e32 v175, v174, v174
	v_fmac_f32_e32 v173, v172, v172
	v_add_f32_e32 v172, v175, v173
	v_add_f32_e32 v171, v172, v171
	ds_bpermute_b32 v172, v168, v171
	s_waitcnt lgkmcnt(0)
	v_add_f32_e32 v171, v171, v172
	ds_bpermute_b32 v172, v169, v171
	s_and_saveexec_b64 s[0:1], vcc
	s_movk_i32 s89, 0x60
	s_mov_b64 s[38:39], s[62:63]
	s_cbranch_execz .LBB0_1298
	s_lshl_b32 s5, s94, 11
	s_add_i32 s5, s4, s5
	v_mul_f32_e32 v170, 0x3c800000, v170
	v_lshl_add_u32 v173, v165, 5, s5
	s_waitcnt lgkmcnt(0)
	v_add_f32_e32 v171, v171, v172
	ds_write_b64 v173, v[170:171]
